# all four GEMM phases: LDS-DMA A operand in full lines into wave-private swizzled slots, B staged behind MFMAs, RoPE table and gate values staged per tile epilogue
# speedup vs baseline: 1.0856x; 1.0387x over previous
.LBB0_166:
	v_mov_b32_e32 v2, v187
	s_movk_i32 s0, 0
	v_writelane_b32 v245, s4, 54
	s_nop 0
	v_cmp_gt_i32_e32 vcc, s0, v2
	v_writelane_b32 v245, s5, 55
	s_and_saveexec_b64 s[4:5], vcc
	s_cbranch_execz .LBB0_179
	v_max_i32_e32 v0, 0x700, v2
	v_sub_u32_e32 v0, v0, v2
	v_add_u32_e32 v0, 0xff, v0
	s_movk_i32 s0, 0xff
	v_cmp_lt_u32_e32 vcc, s0, v0
	s_mov_b64 s[8:9], -1
	s_and_saveexec_b64 s[6:7], vcc
	s_cbranch_execz .LBB0_176
	v_lshrrev_b32_e32 v0, 8, v0
	v_add_u32_e32 v4, -1, v0
	v_add_u32_e32 v3, 0x100, v2
	v_lshrrev_b32_e32 v5, 1, v4
	v_add_u32_e32 v6, 1, v5
	v_cmp_lt_u32_e32 vcc, 13, v4
	v_mov_b32_e32 v9, 0
	v_mov_b64_e32 v[4:5], v[2:3]
	s_and_saveexec_b64 s[8:9], vcc
	s_cbranch_execz .LBB0_172
	v_readlane_b32 s0, v245, 38
	v_readlane_b32 s36, v247, 49
	v_and_b32_e32 v7, -8, v6
	v_lshl_add_u32 v8, v2, 2, s0
	s_mov_b32 s0, 0
	s_mov_b64 s[10:11], 0
	v_mov_b64_e32 v[4:5], v[2:3]
	v_readlane_b32 s40, v247, 53
	v_readlane_b32 s41, v247, 54
	v_readlane_b32 s37, v247, 50
	v_readlane_b32 s38, v247, 51
	v_readlane_b32 s39, v247, 52
	v_readlane_b32 s42, v247, 55
	v_readlane_b32 s43, v247, 56
	v_readlane_b32 s44, v247, 57
	v_readlane_b32 s45, v247, 58
	v_readlane_b32 s46, v247, 59
	v_readlane_b32 s47, v247, 60
	v_readlane_b32 s48, v247, 61
	v_readlane_b32 s49, v247, 62
	v_readlane_b32 s50, v247, 63
	v_readlane_b32 s51, v246, 0

.LBB0_179:
	s_or_b64 exec, exec, s[4:5]
	s_movk_i32 s62, 0x78
	v_readlane_b32 s0, v245, 13
	s_cmp_ge_i32 s0, s62
	s_cbranch_scc1 .LBB0_702
	s_mul_i32 s0, s85, 0x280000
	v_readlane_b32 s42, v247, 23
	v_readlane_b32 s43, v247, 24
	s_lshl_b64 s[4:5], s[0:1], 2
	v_mov_b32_e32 v18, v187
	s_add_u32 s63, s42, s4
	s_addc_u32 s64, s43, s5
	v_readlane_b32 s4, v245, 14
	v_readlane_b32 s5, v245, 15
	s_lshl_b64 s[4:5], s[4:5], 2
	s_add_u32 s4, s63, s4
	s_addc_u32 s5, s64, s5
	v_readlane_b32 s6, v246, 7
	v_readlane_b32 s7, v246, 8
	v_readlane_b32 s65, v245, 16
	v_readlane_b32 s34, v245, 13
	v_and_b32_e32 v19, 31, v18
	v_ashrrev_i32_e32 v21, 5, v18
	v_lshlrev_b32_e32 v208, 2, v19
	v_bfe_u32 v209, v18, 5, 1
	v_and_b32_e32 v219, 0xffffffc0, v18
	v_lshlrev_b32_e32 v0, 4, v18
	v_and_b32_e32 v0, 48, v0
	v_add_u32_e32 v220, 0, v0
	v_add_u32_e32 v221, 0xf000, v0
	v_and_b32_e32 v2, 8, v18
	v_cmp_eq_u32_e64 s[36:37], 0, v2
	v_and_b32_e32 v2, 4, v18
	v_cmp_ne_u32_e64 s[38:39], 0, v2
	v_lshlrev_b32_e32 v2, 13, v21
	v_lshl_add_u32 v2, v21, 11, v2
	v_or_b32_e32 v2, v2, v208
	v_lshlrev_b32_e32 v216, 2, v2
	v_readfirstlane_b32 s71, v18
	s_and_b32 s71, s71, 0xc0
	s_lshl_b32 s71, s71, 8
	s_movk_i32 s72, 0x2000
	v_lshrrev_b32_e32 v2, 1, v19
	v_and_b32_e32 v2, 7, v2
	v_xor_b32_e32 v2, v2, v209
	v_lshlrev_b32_e32 v2, 4, v2
	v_lshl_or_b32 v2, v19, 7, v2
	v_or_b32_e32 v194, s71, v2
	v_xor_b32_e32 v195, 32, v194
	v_xor_b32_e32 v196, 64, v194
	v_xor_b32_e32 v197, 0x60, v194
	v_lshrrev_b32_e32 v2, 2, v19
	v_and_b32_e32 v2, 3, v2
	v_xor_b32_e32 v3, v2, v209
	v_lshlrev_b32_e32 v3, 4, v3
	v_lshl_or_b32 v3, v19, 6, v3
	v_add_u32_e32 v198, 0x10000, v3
	v_xor_b32_e32 v199, 32, v198
	v_lshrrev_b32_e32 v3, 1, v21
	v_xor_b32_e32 v3, v3, v2
	v_lshlrev_b32_e32 v3, 4, v3
	v_and_b32_e32 v4, 1, v21
	v_lshl_or_b32 v3, v4, 3, v3
	v_lshl_or_b32 v3, v19, 6, v3
	v_add_u32_e32 v215, 0x10000, v3
	v_and_b32_e32 v2, 7, v18
	v_bfe_u32 v3, v18, 4, 2
	v_xor_b32_e32 v2, v2, v3
	v_lshlrev_b32_e32 v206, 4, v2
	v_xor_b32_e32 v207, 64, v206
	s_add_u32 s76, s6, 0xfffff000
	s_addc_u32 s77, s7, -1
	v_lshrrev_b32_e32 v2, 3, v18
	v_and_b32_e32 v2, 7, v2
	v_and_b32_e32 v3, 0xc0, v18
	v_or_b32_e32 v2, v2, v3
	v_lshl_add_u32 v162, v2, 11, v206
	v_lshl_add_u32 v163, v2, 11, v207
	v_lshl_add_u32 v164, v2, 11, v206
	v_lshl_add_u32 v165, v2, 11, v207
	v_lshl_add_u32 v166, v2, 11, v206
	v_lshl_add_u32 v167, v2, 11, v207
	v_lshl_add_u32 v168, v2, 11, v206
	v_lshl_add_u32 v169, v2, 11, v207
	v_add_u32_e32 v162, 0x1000, v162
	v_add_u32_e32 v163, 0x4c00, v163
	v_add_u32_e32 v164, 0x8800, v164
	v_add_u32_e32 v165, 0xc400, v165
	v_add_u32_e32 v166, 0x11000, v166
	v_add_u32_e32 v167, 0x14c00, v167
	v_add_u32_e32 v168, 0x18800, v168
	v_add_u32_e32 v169, 0x1c400, v169
	s_lshl_b32 s0, s65, 1
	s_and_b32 s74, s0, 30
	s_lshl_b32 s74, s74, 6
	s_add_u32 s74, s76, s74
	s_addc_u32 s75, s77, 0
	s_mov_b32 m0, s71
	s_nop 0
	global_load_lds_dwordx4 v162, s[74:75]
	global_load_lds_dwordx4 v163, s[74:75] offset:1024
	global_load_lds_dwordx4 v164, s[74:75] offset:2048
	global_load_lds_dwordx4 v165, s[74:75] offset:3072
	s_add_u32 m0, m0, 0x1000
	s_nop 0
	global_load_lds_dwordx4 v166, s[74:75]
	global_load_lds_dwordx4 v167, s[74:75] offset:1024
	global_load_lds_dwordx4 v168, s[74:75] offset:2048
	global_load_lds_dwordx4 v169, s[74:75] offset:3072
	s_and_b32 s48, s0, 31
	s_mul_i32 s48, s48, 0x50000
	s_add_u32 s48, s4, s48
	s_addc_u32 s49, s5, 0
	s_add_u32 s50, s48, 0x2800
	s_addc_u32 s51, s49, 0
	s_add_u32 s52, s48, 0x5000
	s_addc_u32 s53, s49, 0
	s_add_u32 s54, s48, 0x7800
	s_addc_u32 s55, s49, 0
	global_load_dwordx4 v[130:133], v216, s[48:49]
	global_load_dwordx4 v[134:137], v216, s[50:51]
	global_load_dwordx4 v[138:141], v216, s[52:53]
	global_load_dwordx4 v[142:145], v216, s[54:55]
	s_add_i32 s0, s0, 1
	s_and_b32 s48, s0, 31
	s_mul_i32 s48, s48, 0x50000
	s_add_u32 s48, s4, s48
	s_addc_u32 s49, s5, 0
	s_add_u32 s50, s48, 0x2800
	s_addc_u32 s51, s49, 0
	s_add_u32 s52, s48, 0x5000
	s_addc_u32 s53, s49, 0
	s_add_u32 s54, s48, 0x7800
	s_addc_u32 s55, s49, 0
	global_load_dwordx4 v[146:149], v216, s[48:49]
	global_load_dwordx4 v[150:153], v216, s[50:51]
	global_load_dwordx4 v[154:157], v216, s[52:53]
	global_load_dwordx4 v[158:161], v216, s[54:55]
	s_waitcnt vmcnt(4)
	v_cvt_pk_bf16_f32 v200, v130, v134
	v_cvt_pk_bf16_f32 v201, v138, v142
	v_cvt_pk_bf16_f32 v202, v131, v135
	v_cvt_pk_bf16_f32 v203, v139, v143
	ds_write2st64_b64 v215, v[200:201], v[202:203] offset0:0 offset1:4
	v_cvt_pk_bf16_f32 v204, v132, v136
	v_cvt_pk_bf16_f32 v205, v140, v144
	v_cvt_pk_bf16_f32 v200, v133, v137
	v_cvt_pk_bf16_f32 v201, v141, v145
	ds_write2st64_b64 v215, v[204:205], v[200:201] offset0:8 offset1:12
	s_add_i32 s0, s0, 1
	s_and_b32 s48, s0, 31
	s_mul_i32 s48, s48, 0x50000
	s_add_u32 s48, s4, s48
	s_addc_u32 s49, s5, 0
	s_add_u32 s50, s48, 0x2800
	s_addc_u32 s51, s49, 0
	s_add_u32 s52, s48, 0x5000
	s_addc_u32 s53, s49, 0
	s_add_u32 s54, s48, 0x7800
	s_addc_u32 s55, s49, 0
	global_load_dwordx4 v[130:133], v216, s[48:49]
	global_load_dwordx4 v[134:137], v216, s[50:51]
	global_load_dwordx4 v[138:141], v216, s[52:53]
	global_load_dwordx4 v[142:145], v216, s[54:55]
	ds_read_b128 v[230:233], v194
	ds_read_b128 v[234:237], v194 offset:4096
	s_branch .LBB0_182

.LBB0_184:
	v_mov_b32_e32 v2, 0
	s_mov_b32 s15, 0
	s_mov_b32 s70, 2
	s_movk_i32 s72, 0x2000
	v_readfirstlane_b32 s71, v187
	s_and_b32 s71, s71, 0xc0
	s_lshl_b32 s71, s71, 8
	s_add_u32 s76, s6, 0xfffff000
	s_addc_u32 s77, s7, -1
	v_mov_b32_e32 v3, v2
	v_mov_b32_e32 v4, v2
	v_mov_b32_e32 v5, v2
	v_mov_b32_e32 v6, v2
	v_mov_b32_e32 v7, v2
	v_mov_b32_e32 v8, v2
	v_mov_b32_e32 v9, v2
	v_mov_b32_e32 v10, v2
	v_mov_b32_e32 v11, v2
	v_mov_b32_e32 v12, v2
	v_mov_b32_e32 v13, v2
	v_mov_b32_e32 v14, v2
	v_mov_b32_e32 v15, v2
	v_mov_b32_e32 v16, v2
	v_mov_b32_e32 v17, v2
	v_mov_b32_e32 v34, v2
	v_mov_b32_e32 v35, v2
	v_mov_b32_e32 v36, v2
	v_mov_b32_e32 v37, v2
	v_mov_b32_e32 v38, v2
	v_mov_b32_e32 v39, v2
	v_mov_b32_e32 v40, v2
	v_mov_b32_e32 v41, v2
	v_mov_b32_e32 v42, v2
	v_mov_b32_e32 v43, v2
	v_mov_b32_e32 v44, v2
	v_mov_b32_e32 v45, v2
	v_mov_b32_e32 v46, v2
	v_mov_b32_e32 v47, v2
	v_mov_b32_e32 v48, v2
	v_mov_b32_e32 v49, v2
	v_mov_b32_e32 v18, v2
	v_mov_b32_e32 v19, v2
	v_mov_b32_e32 v20, v2
	v_mov_b32_e32 v21, v2
	v_mov_b32_e32 v22, v2
	v_mov_b32_e32 v23, v2
	v_mov_b32_e32 v24, v2
	v_mov_b32_e32 v25, v2
	v_mov_b32_e32 v26, v2
	v_mov_b32_e32 v27, v2
	v_mov_b32_e32 v28, v2
	v_mov_b32_e32 v29, v2
	v_mov_b32_e32 v30, v2
	v_mov_b32_e32 v31, v2
	v_mov_b32_e32 v32, v2
	v_mov_b32_e32 v33, v2
	v_mov_b32_e32 v50, v2
	v_mov_b32_e32 v51, v2
	v_mov_b32_e32 v52, v2
	v_mov_b32_e32 v53, v2
	v_mov_b32_e32 v54, v2
	v_mov_b32_e32 v55, v2
	v_mov_b32_e32 v56, v2
	v_mov_b32_e32 v57, v2
	v_mov_b32_e32 v58, v2
	v_mov_b32_e32 v59, v2
	v_mov_b32_e32 v60, v2
	v_mov_b32_e32 v61, v2
	v_mov_b32_e32 v62, v2
	v_mov_b32_e32 v63, v2
	v_mov_b32_e32 v64, v2
	v_mov_b32_e32 v65, v2
	v_mov_b32_e32 v66, v2
	v_mov_b32_e32 v67, v2
	v_mov_b32_e32 v68, v2
	v_mov_b32_e32 v69, v2
	v_mov_b32_e32 v70, v2
	v_mov_b32_e32 v71, v2
	v_mov_b32_e32 v72, v2
	v_mov_b32_e32 v73, v2
	v_mov_b32_e32 v74, v2
	v_mov_b32_e32 v75, v2
	v_mov_b32_e32 v76, v2
	v_mov_b32_e32 v77, v2
	v_mov_b32_e32 v78, v2
	v_mov_b32_e32 v79, v2
	s_waitcnt vmcnt(23)
	v_mov_b32_e32 v80, v2
	v_mov_b32_e32 v81, v2
	v_mov_b32_e32 v98, v2
	v_mov_b32_e32 v99, v2
	v_mov_b32_e32 v100, v2
	v_mov_b32_e32 v101, v2
	v_mov_b32_e32 v102, v2
	v_mov_b32_e32 v103, v2
	v_mov_b32_e32 v104, v2
	v_mov_b32_e32 v105, v2
	v_mov_b32_e32 v106, v2
	v_mov_b32_e32 v107, v2
	v_mov_b32_e32 v108, v2
	v_mov_b32_e32 v109, v2
	v_mov_b32_e32 v110, v2
	v_mov_b32_e32 v111, v2
	v_mov_b32_e32 v112, v2
	v_mov_b32_e32 v113, v2
	v_mov_b32_e32 v82, v2
	v_mov_b32_e32 v83, v2
	s_waitcnt vmcnt(22)
	v_mov_b32_e32 v84, v2
	v_mov_b32_e32 v85, v2
	v_mov_b32_e32 v86, v2
	v_mov_b32_e32 v87, v2
	s_waitcnt vmcnt(21)
	v_mov_b32_e32 v88, v2
	v_mov_b32_e32 v89, v2
	v_mov_b32_e32 v90, v2
	v_mov_b32_e32 v91, v2
	s_waitcnt vmcnt(20)
	v_mov_b32_e32 v92, v2
	v_mov_b32_e32 v93, v2
	v_mov_b32_e32 v94, v2
	v_mov_b32_e32 v95, v2
	v_mov_b32_e32 v96, v2
	v_mov_b32_e32 v97, v2
	v_mov_b32_e32 v114, v2
	v_mov_b32_e32 v115, v2
	v_mov_b32_e32 v116, v2
	v_mov_b32_e32 v117, v2
	v_mov_b32_e32 v118, v2
	v_mov_b32_e32 v119, v2
	v_mov_b32_e32 v120, v2
	v_mov_b32_e32 v121, v2
	v_mov_b32_e32 v122, v2
	v_mov_b32_e32 v123, v2
	v_mov_b32_e32 v124, v2
	v_mov_b32_e32 v125, v2
	v_mov_b32_e32 v126, v2
	v_mov_b32_e32 v127, v2
	v_mov_b32_e32 v128, v2
	v_mov_b32_e32 v129, v2
	s_branch .Lg1_loop
.Lg1_switch:
	s_mov_b64 s[4:5], s[12:13]
	s_mov_b64 s[6:7], s[10:11]
	s_add_u32 s76, s6, 0xfffff000
	s_addc_u32 s77, s7, -1
	s_mov_b32 s65, s14
	s_mov_b32 s70, -2
	s_branch .Lg1_noswitch
.Lg1_loop:
	s_waitcnt lgkmcnt(0)
	s_barrier
	ds_read_b128 v[238:241], v198
	ds_read_b128 v[170:173], v198 offset:2048
	ds_read_b128 v[174:177], v198 offset:4096
	ds_read_b128 v[190:193], v198 offset:6144
	ds_read_b128 v[248:251], v195
	ds_read_b128 v[252:255], v195 offset:4096
	s_lshl_b32 s0, s65, 1
	s_add_i32 s0, s0, s70
	s_and_b32 s74, s0, 30
	s_lshl_b32 s74, s74, 6
	s_add_u32 s74, s76, s74
	s_addc_u32 s75, s77, 0
	s_add_i32 s32, s71, s72
	s_mov_b32 m0, s32
	s_waitcnt lgkmcnt(5)
	v_mfma_f32_32x32x16_bf16 v[114:129], v[230:233], v[238:241], v[114:129]
	global_load_lds_dwordx4 v162, s[74:75]
	v_mfma_f32_32x32x16_bf16 v[50:65], v[234:237], v[238:241], v[50:65]
	ds_read_b128 v[238:241], v199
	s_waitcnt lgkmcnt(5)
	v_mfma_f32_32x32x16_bf16 v[82:97], v[230:233], v[170:173], v[82:97]
	global_load_lds_dwordx4 v163, s[74:75] offset:1024
	v_mfma_f32_32x32x16_bf16 v[18:33], v[234:237], v[170:173], v[18:33]
	ds_read_b128 v[170:173], v199 offset:2048
	s_waitcnt lgkmcnt(5)
	v_mfma_f32_32x32x16_bf16 v[98:113], v[230:233], v[174:177], v[98:113]
	global_load_lds_dwordx4 v164, s[74:75] offset:2048
	v_mfma_f32_32x32x16_bf16 v[34:49], v[234:237], v[174:177], v[34:49]
	ds_read_b128 v[174:177], v199 offset:4096
	s_waitcnt lgkmcnt(5)
	v_mfma_f32_32x32x16_bf16 v[66:81], v[230:233], v[190:193], v[66:81]
	global_load_lds_dwordx4 v165, s[74:75] offset:3072
	s_add_u32 m0, m0, 0x1000
	v_mfma_f32_32x32x16_bf16 v[2:17], v[234:237], v[190:193], v[2:17]
	ds_read_b128 v[190:193], v199 offset:6144
	ds_read_b128 v[230:233], v196
	ds_read_b128 v[234:237], v196 offset:4096
	s_waitcnt vmcnt(8)
	v_cvt_pk_bf16_f32 v200, v146, v150
	v_cvt_pk_bf16_f32 v201, v154, v158
	v_cvt_pk_bf16_f32 v202, v147, v151
	v_cvt_pk_bf16_f32 v203, v155, v159
	s_waitcnt lgkmcnt(5)
	v_mfma_f32_32x32x16_bf16 v[114:129], v[248:251], v[238:241], v[114:129]
	global_load_lds_dwordx4 v166, s[74:75]
	ds_write2st64_b64 v215, v[200:201], v[202:203] offset0:16 offset1:20
	v_cvt_pk_bf16_f32 v204, v148, v152
	v_cvt_pk_bf16_f32 v205, v156, v160
	v_cvt_pk_bf16_f32 v200, v149, v153
	v_cvt_pk_bf16_f32 v201, v157, v161
	v_mfma_f32_32x32x16_bf16 v[50:65], v[252:255], v[238:241], v[50:65]
	global_load_lds_dwordx4 v167, s[74:75] offset:1024
	ds_write2st64_b64 v215, v[204:205], v[200:201] offset0:24 offset1:28
	s_add_i32 s0, s0, 1
	s_and_b32 s48, s0, 31
	s_mul_i32 s48, s48, 0x50000
	s_add_u32 s48, s4, s48
	s_addc_u32 s49, s5, 0
	s_add_u32 s50, s48, 0x2800
	s_addc_u32 s51, s49, 0
	s_add_u32 s52, s48, 0x5000
	s_addc_u32 s53, s49, 0
	s_add_u32 s54, s48, 0x7800
	s_addc_u32 s55, s49, 0
	s_waitcnt lgkmcnt(6)
	v_mfma_f32_32x32x16_bf16 v[82:97], v[248:251], v[170:173], v[82:97]
	global_load_lds_dwordx4 v168, s[74:75] offset:2048
	v_mfma_f32_32x32x16_bf16 v[18:33], v[252:255], v[170:173], v[18:33]
	global_load_lds_dwordx4 v169, s[74:75] offset:3072
	s_waitcnt lgkmcnt(5)
	v_mfma_f32_32x32x16_bf16 v[98:113], v[248:251], v[174:177], v[98:113]
	global_load_dwordx4 v[146:149], v216, s[48:49]
	v_mfma_f32_32x32x16_bf16 v[34:49], v[252:255], v[174:177], v[34:49]
	global_load_dwordx4 v[150:153], v216, s[50:51]
	s_waitcnt lgkmcnt(4)
	v_mfma_f32_32x32x16_bf16 v[66:81], v[248:251], v[190:193], v[66:81]
	global_load_dwordx4 v[154:157], v216, s[52:53]
	v_mfma_f32_32x32x16_bf16 v[2:17], v[252:255], v[190:193], v[2:17]
	global_load_dwordx4 v[158:161], v216, s[54:55]
	s_waitcnt lgkmcnt(0)
	s_barrier
	ds_read_b128 v[238:241], v198 offset:8192
	ds_read_b128 v[170:173], v198 offset:10240
	ds_read_b128 v[174:177], v198 offset:12288
	ds_read_b128 v[190:193], v198 offset:14336
	ds_read_b128 v[248:251], v197
	ds_read_b128 v[252:255], v197 offset:4096
	s_cmp_eq_u32 s15, 14
	s_cbranch_scc1 .Lg1_switch
.Lg1_noswitch:
	s_waitcnt lgkmcnt(5)
	v_mfma_f32_32x32x16_bf16 v[114:129], v[230:233], v[238:241], v[114:129]
	v_mfma_f32_32x32x16_bf16 v[50:65], v[234:237], v[238:241], v[50:65]
	ds_read_b128 v[238:241], v199 offset:8192
	s_waitcnt lgkmcnt(5)
	v_mfma_f32_32x32x16_bf16 v[82:97], v[230:233], v[170:173], v[82:97]
	v_mfma_f32_32x32x16_bf16 v[18:33], v[234:237], v[170:173], v[18:33]
	ds_read_b128 v[170:173], v199 offset:10240
	s_waitcnt lgkmcnt(5)
	v_mfma_f32_32x32x16_bf16 v[98:113], v[230:233], v[174:177], v[98:113]
	v_mfma_f32_32x32x16_bf16 v[34:49], v[234:237], v[174:177], v[34:49]
	ds_read_b128 v[174:177], v199 offset:12288
	s_waitcnt lgkmcnt(5)
	v_mfma_f32_32x32x16_bf16 v[66:81], v[230:233], v[190:193], v[66:81]
	v_mfma_f32_32x32x16_bf16 v[2:17], v[234:237], v[190:193], v[2:17]
	ds_read_b128 v[190:193], v199 offset:14336
	s_waitcnt vmcnt(12)
	v_cvt_pk_bf16_f32 v200, v130, v134
	v_cvt_pk_bf16_f32 v201, v138, v142
	v_cvt_pk_bf16_f32 v202, v131, v135
	v_cvt_pk_bf16_f32 v203, v139, v143
	s_waitcnt lgkmcnt(3)
	v_mfma_f32_32x32x16_bf16 v[114:129], v[248:251], v[238:241], v[114:129]
	ds_write2st64_b64 v215, v[200:201], v[202:203] offset0:0 offset1:4
	v_cvt_pk_bf16_f32 v204, v132, v136
	v_cvt_pk_bf16_f32 v205, v140, v144
	v_cvt_pk_bf16_f32 v200, v133, v137
	v_cvt_pk_bf16_f32 v201, v141, v145
	v_mfma_f32_32x32x16_bf16 v[50:65], v[252:255], v[238:241], v[50:65]
	ds_write2st64_b64 v215, v[204:205], v[200:201] offset0:8 offset1:12
	s_lshl_b32 s0, s65, 1
	s_add_i32 s0, s0, s70
	s_add_i32 s0, s0, 2
	s_and_b32 s48, s0, 31
	s_mul_i32 s48, s48, 0x50000
	s_add_u32 s48, s4, s48
	s_addc_u32 s49, s5, 0
	s_add_u32 s50, s48, 0x2800
	s_addc_u32 s51, s49, 0
	s_add_u32 s52, s48, 0x5000
	s_addc_u32 s53, s49, 0
	s_add_u32 s54, s48, 0x7800
	s_addc_u32 s55, s49, 0
	s_waitcnt lgkmcnt(4)
	v_mfma_f32_32x32x16_bf16 v[82:97], v[248:251], v[170:173], v[82:97]
	v_mfma_f32_32x32x16_bf16 v[18:33], v[252:255], v[170:173], v[18:33]
	s_waitcnt lgkmcnt(3)
	v_mfma_f32_32x32x16_bf16 v[98:113], v[248:251], v[174:177], v[98:113]
	global_load_dwordx4 v[130:133], v216, s[48:49]
	v_mfma_f32_32x32x16_bf16 v[34:49], v[252:255], v[174:177], v[34:49]
	global_load_dwordx4 v[134:137], v216, s[50:51]
	s_waitcnt lgkmcnt(2)
	v_mfma_f32_32x32x16_bf16 v[66:81], v[248:251], v[190:193], v[66:81]
	global_load_dwordx4 v[138:141], v216, s[52:53]
	v_mfma_f32_32x32x16_bf16 v[2:17], v[252:255], v[190:193], v[2:17]
	global_load_dwordx4 v[142:145], v216, s[54:55]
	s_xor_b32 s72, s72, 0x2000
	v_xor_b32_e32 v194, 0x2000, v194
	v_xor_b32_e32 v195, 0x2000, v195
	v_xor_b32_e32 v196, 0x2000, v196
	v_xor_b32_e32 v197, 0x2000, v197
	s_waitcnt vmcnt(8)
	ds_read_b128 v[230:233], v194
	ds_read_b128 v[234:237], v194 offset:4096
	s_add_i32 s70, s70, 2
	s_add_i32 s15, s15, 1
	s_cmp_lt_u32 s15, 16
	s_cbranch_scc1 .Lg1_loop
	s_branch .LBB0_189
.LBB0_189:
	s_mul_hi_u32 s0, s34, 0xaaaaaaab
	s_lshr_b32 s12, s0, 2
	s_mul_i32 s0, s12, 6
	s_sub_i32 s0, s34, s0
	v_readlane_b32 s10, v246, 6
	s_add_i32 s13, s0, s10
	v_mov_b32_e32 v0, v209
	s_cmp_lt_u32 s13, 16
	s_cselect_b64 s[42:43], -1, 0
	s_cmp_gt_u32 s13, 15
	s_cselect_b64 s[10:11], -1, 0
	v_sub_co_u32_e64 v178, s[14:15], s34, 30
	v_lshlrev_b32_e32 v0, 2, v0
	v_add_u32_e32 v224, v0, v219
	s_and_b64 s[10:11], s[14:15], s[10:11]
	s_cmp_lg_u64 s[10:11], 0
	s_cbranch_scc0 .Lg1_norope
	s_barrier
	v_readlane_b32 s74, v247, 53
	v_readlane_b32 s75, v247, 54
	v_lshlrev_b32_e32 v174, 5, v187
	s_nop 4
	global_load_dwordx4 v[238:241], v174, s[74:75]
	global_load_dwordx4 v[170:173], v174, s[74:75] offset:16
	s_waitcnt vmcnt(0)
	ds_write_b128 v174, v[238:241] offset:57344
	ds_write_b128 v174, v[170:173] offset:57360
	s_waitcnt lgkmcnt(0)
	s_barrier
.Lg1_norope:
	v_readfirstlane_b32 s0, v178
	v_lshl_add_u32 v222, s13, 8, v224
	v_cndmask_b32_e64 v178, 0, 1, s[10:11]
	v_mov_b32_e32 v202, v114
	v_mov_b32_e32 v203, v82
	v_mov_b32_e32 v200, v98
	v_mov_b32_e32 v201, v66
	v_cmp_ne_u32_e64 s[40:41], 1, v178
	s_andn2_b64 vcc, exec, s[10:11]
	v_bfe_u32 v223, v222, 6, 5
	s_cbranch_vccnz .LBB0_195
	v_and_b32_e32 v0, 60, v0
	v_cndmask_b32_e64 v0, v0, v223, s[36:37]
	v_lshlrev_b32_e32 v0, 6, v0
	v_add_u32_e32 v178, v220, v0
	v_add_u32_e32 v0, v221, v0
	v_and_b32_e32 v179, 64, v213
	ds_read_b128 v[204:207], v0
	v_xor_b32_e32 v0, 4, v213
	v_add_u32_e32 v179, 64, v179
	v_cmp_lt_i32_e32 vcc, v0, v179
	ds_read_b128 v[178:181], v178 offset:57344
	s_nop 0
	v_cndmask_b32_e32 v0, v213, v0, vcc
	v_lshlrev_b32_e32 v0, 2, v0
	ds_bpermute_b32 v226, v0, v114
	ds_bpermute_b32 v227, v0, v82
	ds_bpermute_b32 v228, v0, v98
	ds_bpermute_b32 v229, v0, v66
	s_waitcnt lgkmcnt(2)
	v_pk_mul_f32 v[204:205], v[204:205], v[226:227]
	s_waitcnt lgkmcnt(0)
	v_pk_mul_f32 v[206:207], v[206:207], v[228:229]
	s_and_saveexec_b64 s[10:11], s[38:39]
	s_xor_b64 s[10:11], exec, s[10:11]
	v_pk_fma_f32 v[202:203], v[202:203], v[178:179], v[204:205]
	v_pk_fma_f32 v[200:201], v[200:201], v[180:181], v[206:207]
	s_andn2_saveexec_b64 s[10:11], s[10:11]
	v_pk_fma_f32 v[202:203], v[202:203], v[178:179], v[204:205] neg_lo:[0,0,1] neg_hi:[0,0,1]
	v_pk_fma_f32 v[200:201], v[200:201], v[180:181], v[206:207] neg_lo:[0,0,1] neg_hi:[0,0,1]
	s_or_b64 exec, exec, s[10:11]

.LBB0_205:
	v_or_b32_e32 v200, 1, v222
	v_mov_b32_e32 v82, v115
	s_and_b64 vcc, exec, s[40:41]
	v_mov_b32_e32 v66, v99
	s_cbranch_vccnz .LBB0_211
	v_and_b32_e32 v98, 61, v200
	v_cndmask_b32_e64 v98, v98, v223, s[36:37]
	v_lshlrev_b32_e32 v98, 6, v98
	v_add_u32_e32 v178, v220, v98
	v_add_u32_e32 v98, v221, v98
	v_and_b32_e32 v114, 64, v213
	ds_read_b128 v[202:205], v98
	ds_read_b128 v[178:181], v178 offset:57344
	v_xor_b32_e32 v98, 4, v213
	v_add_u32_e32 v114, 64, v114
	v_cmp_lt_i32_e32 vcc, v98, v114
	s_nop 1
	v_cndmask_b32_e32 v98, v213, v98, vcc
	v_lshlrev_b32_e32 v98, 2, v98
	ds_bpermute_b32 v114, v98, v115
	ds_bpermute_b32 v115, v98, v83
	ds_bpermute_b32 v206, v98, v99
	ds_bpermute_b32 v207, v98, v67
	s_waitcnt lgkmcnt(2)
	v_pk_mul_f32 v[98:99], v[202:203], v[114:115]
	s_waitcnt lgkmcnt(0)
	v_pk_mul_f32 v[114:115], v[204:205], v[206:207]
	s_and_saveexec_b64 s[50:51], s[38:39]
	s_xor_b64 s[50:51], exec, s[50:51]
	v_pk_fma_f32 v[82:83], v[82:83], v[178:179], v[98:99]
	v_pk_fma_f32 v[66:67], v[66:67], v[180:181], v[114:115]
	s_andn2_saveexec_b64 s[50:51], s[50:51]
	v_pk_fma_f32 v[82:83], v[82:83], v[178:179], v[98:99] neg_lo:[0,0,1] neg_hi:[0,0,1]
	v_pk_fma_f32 v[66:67], v[66:67], v[180:181], v[114:115] neg_lo:[0,0,1] neg_hi:[0,0,1]
	s_or_b64 exec, exec, s[50:51]

.LBB0_221:
	v_or_b32_e32 v202, 2, v222
	v_mov_b32_e32 v82, v116
	v_mov_b32_e32 v83, v84
	v_mov_b32_e32 v66, v100
	s_and_b64 vcc, exec, s[40:41]
	v_mov_b32_e32 v67, v68
	s_cbranch_vccnz .LBB0_227
	v_and_b32_e32 v98, 62, v202
	v_cndmask_b32_e64 v98, v98, v223, s[36:37]
	v_lshlrev_b32_e32 v98, 6, v98
	v_add_u32_e32 v115, v220, v98
	v_add_u32_e32 v98, v221, v98
	v_and_b32_e32 v99, 64, v213
	ds_read_b128 v[204:207], v98
	v_xor_b32_e32 v98, 4, v213
	v_add_u32_e32 v99, 64, v99
	v_cmp_lt_i32_e32 vcc, v98, v99
	s_nop 1
	v_cndmask_b32_e32 v98, v213, v98, vcc
	v_lshlrev_b32_e32 v178, 2, v98
	ds_bpermute_b32 v98, v178, v116
	ds_bpermute_b32 v99, v178, v84
	ds_bpermute_b32 v200, v178, v100
	ds_bpermute_b32 v201, v178, v68
	ds_read_b128 v[178:181], v115 offset:57344
	s_waitcnt lgkmcnt(3)
	v_pk_mul_f32 v[98:99], v[204:205], v[98:99]
	s_waitcnt lgkmcnt(1)
	v_pk_mul_f32 v[200:201], v[206:207], v[200:201]
	s_and_saveexec_b64 s[50:51], s[38:39]
	s_xor_b64 s[50:51], exec, s[50:51]
	s_cbranch_execz .LBB0_224
	s_waitcnt lgkmcnt(0)
	v_pk_fma_f32 v[82:83], v[82:83], v[178:179], v[98:99]
	v_pk_fma_f32 v[66:67], v[66:67], v[180:181], v[200:201]

.LBB0_237:
	v_or_b32_e32 v116, 3, v222
	v_mov_b32_e32 v84, v117
	s_and_b64 vcc, exec, s[40:41]
	v_mov_b32_e32 v68, v101
	s_cbranch_vccnz .LBB0_243
	v_and_b32_e32 v66, 63, v116
	v_cndmask_b32_e64 v66, v66, v223, s[36:37]
	v_lshlrev_b32_e32 v66, 6, v66
	v_add_u32_e32 v98, v220, v66
	v_add_u32_e32 v66, v221, v66
	v_and_b32_e32 v67, 64, v213
	ds_read_b128 v[178:181], v66
	v_xor_b32_e32 v66, 4, v213
	v_add_u32_e32 v67, 64, v67
	v_cmp_lt_i32_e32 vcc, v66, v67
	s_nop 1
	v_cndmask_b32_e32 v66, v213, v66, vcc
	v_lshlrev_b32_e32 v83, 2, v66
	ds_bpermute_b32 v66, v83, v117
	ds_bpermute_b32 v67, v83, v85
	ds_bpermute_b32 v82, v83, v101
	ds_bpermute_b32 v83, v83, v69
	ds_read_b128 v[98:101], v98 offset:57344
	s_waitcnt lgkmcnt(3)
	v_pk_mul_f32 v[66:67], v[178:179], v[66:67]
	s_waitcnt lgkmcnt(1)
	v_pk_mul_f32 v[82:83], v[180:181], v[82:83]
	s_and_saveexec_b64 s[50:51], s[38:39]
	s_xor_b64 s[50:51], exec, s[50:51]
	s_cbranch_execz .LBB0_240
	s_waitcnt lgkmcnt(0)
	v_pk_fma_f32 v[84:85], v[84:85], v[98:99], v[66:67]
	v_pk_fma_f32 v[68:69], v[68:69], v[100:101], v[82:83]

.LBB0_253:
	v_add_u32_e32 v116, 8, v222
	v_mov_b32_e32 v84, v118
	v_mov_b32_e32 v85, v86
	v_mov_b32_e32 v82, v102
	s_and_b64 vcc, exec, s[40:41]
	v_mov_b32_e32 v83, v70
	s_cbranch_vccnz .LBB0_259
	v_bfe_u32 v66, v116, 6, 5
	v_and_b32_e32 v67, 60, v116
	v_cndmask_b32_e64 v66, v67, v66, s[36:37]
	v_lshlrev_b32_e32 v66, 6, v66
	v_add_u32_e32 v67, v220, v66
	v_add_u32_e32 v66, v221, v66
	v_and_b32_e32 v68, 64, v213
	s_waitcnt lgkmcnt(0)
	ds_read_b128 v[98:101], v66
	v_xor_b32_e32 v66, 4, v213
	v_add_u32_e32 v68, 64, v68
	v_cmp_lt_i32_e32 vcc, v66, v68
	s_nop 1
	v_cndmask_b32_e32 v66, v213, v66, vcc
	v_lshlrev_b32_e32 v66, 2, v66
	ds_bpermute_b32 v178, v66, v118
	ds_bpermute_b32 v179, v66, v86
	ds_bpermute_b32 v180, v66, v102
	ds_bpermute_b32 v181, v66, v70
	ds_read_b128 v[66:69], v67 offset:57344
	s_waitcnt lgkmcnt(3)
	v_pk_mul_f32 v[98:99], v[98:99], v[178:179]
	s_waitcnt lgkmcnt(1)
	v_pk_mul_f32 v[100:101], v[100:101], v[180:181]
	s_and_saveexec_b64 s[50:51], s[38:39]
	s_xor_b64 s[50:51], exec, s[50:51]
	s_cbranch_execz .LBB0_256
	s_waitcnt lgkmcnt(0)
	v_pk_fma_f32 v[84:85], v[84:85], v[66:67], v[98:99]
	v_pk_fma_f32 v[82:83], v[82:83], v[68:69], v[100:101]

.LBB0_269:
	v_add_u32_e32 v98, 9, v222
	v_mov_b32_e32 v86, v119
	s_and_b64 vcc, exec, s[40:41]
	v_mov_b32_e32 v70, v103
	s_cbranch_vccnz .LBB0_275
	v_bfe_u32 v66, v98, 6, 5
	v_and_b32_e32 v67, 61, v98
	v_cndmask_b32_e64 v66, v67, v66, s[36:37]
	v_lshlrev_b32_e32 v66, 6, v66
	v_add_u32_e32 v67, v220, v66
	v_add_u32_e32 v66, v221, v66
	v_and_b32_e32 v68, 64, v213
	ds_read_b128 v[82:85], v66
	v_xor_b32_e32 v66, 4, v213
	v_add_u32_e32 v68, 64, v68
	v_cmp_lt_i32_e32 vcc, v66, v68
	s_nop 1
	v_cndmask_b32_e32 v66, v213, v66, vcc
	v_lshlrev_b32_e32 v66, 2, v66
	ds_bpermute_b32 v100, v66, v119
	ds_bpermute_b32 v101, v66, v87
	ds_bpermute_b32 v102, v66, v103
	ds_bpermute_b32 v103, v66, v71
	ds_read_b128 v[66:69], v67 offset:57344
	s_waitcnt lgkmcnt(3)
	v_pk_mul_f32 v[82:83], v[82:83], v[100:101]
	s_waitcnt lgkmcnt(1)
	v_pk_mul_f32 v[84:85], v[84:85], v[102:103]
	s_and_saveexec_b64 s[50:51], s[38:39]
	s_xor_b64 s[50:51], exec, s[50:51]
	s_cbranch_execz .LBB0_272
	s_waitcnt lgkmcnt(0)
	v_pk_fma_f32 v[86:87], v[86:87], v[66:67], v[82:83]
	v_pk_fma_f32 v[70:71], v[70:71], v[68:69], v[84:85]

.LBB0_285:
	v_add_u32_e32 v98, 10, v222
	v_mov_b32_e32 v82, v120
	v_mov_b32_e32 v83, v88
	v_mov_b32_e32 v70, v104
	s_and_b64 vcc, exec, s[40:41]
	v_mov_b32_e32 v71, v72
	s_cbranch_vccnz .LBB0_291
	v_bfe_u32 v66, v98, 6, 5
	v_and_b32_e32 v67, 62, v98
	v_cndmask_b32_e64 v66, v67, v66, s[36:37]
	v_lshlrev_b32_e32 v66, 6, v66
	v_add_u32_e32 v67, v220, v66
	v_add_u32_e32 v66, v221, v66
	v_and_b32_e32 v68, 64, v213
	ds_read_b128 v[84:87], v66
	v_xor_b32_e32 v66, 4, v213
	v_add_u32_e32 v68, 64, v68
	v_cmp_lt_i32_e32 vcc, v66, v68
	s_nop 1
	v_cndmask_b32_e32 v66, v213, v66, vcc
	v_lshlrev_b32_e32 v66, 2, v66
	ds_bpermute_b32 v100, v66, v120
	ds_bpermute_b32 v101, v66, v88
	ds_bpermute_b32 v102, v66, v104
	ds_bpermute_b32 v103, v66, v72
	ds_read_b128 v[66:69], v67 offset:57344
	s_waitcnt lgkmcnt(3)
	v_pk_mul_f32 v[84:85], v[84:85], v[100:101]
	s_waitcnt lgkmcnt(1)
	v_pk_mul_f32 v[86:87], v[86:87], v[102:103]
	s_and_saveexec_b64 s[50:51], s[38:39]
	s_xor_b64 s[50:51], exec, s[50:51]
	s_cbranch_execz .LBB0_288
	s_waitcnt lgkmcnt(0)
	v_pk_fma_f32 v[82:83], v[82:83], v[66:67], v[84:85]
	v_pk_fma_f32 v[70:71], v[70:71], v[68:69], v[86:87]

.LBB0_301:
	v_add_u32_e32 v84, 11, v222
	v_mov_b32_e32 v88, v121
	s_and_b64 vcc, exec, s[40:41]
	v_mov_b32_e32 v72, v105
	s_cbranch_vccnz .LBB0_307
	v_bfe_u32 v66, v84, 6, 5
	v_and_b32_e32 v67, 63, v84
	v_cndmask_b32_e64 v66, v67, v66, s[36:37]
	v_lshlrev_b32_e32 v66, 6, v66
	v_add_u32_e32 v67, v220, v66
	v_add_u32_e32 v66, v221, v66
	v_and_b32_e32 v68, 64, v213
	ds_read_b128 v[98:101], v66
	v_xor_b32_e32 v66, 4, v213
	v_add_u32_e32 v68, 64, v68
	v_cmp_lt_i32_e32 vcc, v66, v68
	s_nop 1
	v_cndmask_b32_e32 v66, v213, v66, vcc
	v_lshlrev_b32_e32 v66, 2, v66
	ds_bpermute_b32 v70, v66, v121
	ds_bpermute_b32 v71, v66, v89
	ds_bpermute_b32 v82, v66, v105
	ds_bpermute_b32 v83, v66, v73
	ds_read_b128 v[66:69], v67 offset:57344
	s_waitcnt lgkmcnt(3)
	v_pk_mul_f32 v[70:71], v[98:99], v[70:71]
	s_waitcnt lgkmcnt(1)
	v_pk_mul_f32 v[82:83], v[100:101], v[82:83]
	s_and_saveexec_b64 s[50:51], s[38:39]
	s_xor_b64 s[50:51], exec, s[50:51]
	s_cbranch_execz .LBB0_304
	s_waitcnt lgkmcnt(0)
	v_pk_fma_f32 v[88:89], v[88:89], v[66:67], v[70:71]
	v_pk_fma_f32 v[72:73], v[72:73], v[68:69], v[82:83]

.LBB0_317:
	v_add_u32_e32 v86, 16, v222
	v_mov_b32_e32 v72, v122
	v_mov_b32_e32 v73, v90
	v_mov_b32_e32 v70, v106
	s_and_b64 vcc, exec, s[40:41]
	v_mov_b32_e32 v71, v74
	s_cbranch_vccnz .LBB0_323
	v_bfe_u32 v66, v86, 6, 5
	v_and_b32_e32 v67, 60, v86
	v_cndmask_b32_e64 v66, v67, v66, s[36:37]
	v_lshlrev_b32_e32 v66, 6, v66
	v_add_u32_e32 v67, v220, v66
	v_add_u32_e32 v66, v221, v66
	v_and_b32_e32 v68, 64, v213
	ds_read_b128 v[82:85], v66
	v_xor_b32_e32 v66, 4, v213
	v_add_u32_e32 v68, 64, v68
	v_cmp_lt_i32_e32 vcc, v66, v68
	s_nop 1
	v_cndmask_b32_e32 v66, v213, v66, vcc
	v_lshlrev_b32_e32 v66, 2, v66
	ds_bpermute_b32 v88, v66, v122
	ds_bpermute_b32 v89, v66, v90
	ds_bpermute_b32 v98, v66, v106
	ds_bpermute_b32 v99, v66, v74
	ds_read_b128 v[66:69], v67 offset:57344
	s_waitcnt lgkmcnt(3)
	v_pk_mul_f32 v[82:83], v[82:83], v[88:89]
	s_waitcnt lgkmcnt(1)
	v_pk_mul_f32 v[84:85], v[84:85], v[98:99]
	s_and_saveexec_b64 s[50:51], s[38:39]
	s_xor_b64 s[50:51], exec, s[50:51]
	s_cbranch_execz .LBB0_320
	s_waitcnt lgkmcnt(0)
	v_pk_fma_f32 v[72:73], v[72:73], v[66:67], v[82:83]
	v_pk_fma_f32 v[70:71], v[70:71], v[68:69], v[84:85]

.LBB0_333:
	v_add_u32_e32 v82, 17, v222
	v_mov_b32_e32 v90, v123
	s_and_b64 vcc, exec, s[40:41]
	v_mov_b32_e32 v74, v107
	s_cbranch_vccnz .LBB0_339
	v_bfe_u32 v66, v82, 6, 5
	v_and_b32_e32 v67, 61, v82
	v_cndmask_b32_e64 v66, v67, v66, s[36:37]
	v_lshlrev_b32_e32 v66, 6, v66
	v_add_u32_e32 v67, v220, v66
	v_add_u32_e32 v66, v221, v66
	v_and_b32_e32 v68, 64, v213
	ds_read_b128 v[70:73], v66
	v_xor_b32_e32 v66, 4, v213
	v_add_u32_e32 v68, 64, v68
	v_cmp_lt_i32_e32 vcc, v66, v68
	s_nop 1
	v_cndmask_b32_e32 v66, v213, v66, vcc
	v_lshlrev_b32_e32 v66, 2, v66
	ds_bpermute_b32 v84, v66, v123
	ds_bpermute_b32 v85, v66, v91
	ds_bpermute_b32 v86, v66, v107
	ds_bpermute_b32 v87, v66, v75
	ds_read_b128 v[66:69], v67 offset:57344
	s_waitcnt lgkmcnt(3)
	v_pk_mul_f32 v[70:71], v[70:71], v[84:85]
	s_waitcnt lgkmcnt(1)
	v_pk_mul_f32 v[72:73], v[72:73], v[86:87]
	s_and_saveexec_b64 s[50:51], s[38:39]
	s_xor_b64 s[50:51], exec, s[50:51]
	s_cbranch_execz .LBB0_336
	s_waitcnt lgkmcnt(0)
	v_pk_fma_f32 v[90:91], v[90:91], v[66:67], v[70:71]
	v_pk_fma_f32 v[74:75], v[74:75], v[68:69], v[72:73]

.LBB0_349:
	v_add_u32_e32 v84, 18, v222
	v_mov_b32_e32 v72, v124
	v_mov_b32_e32 v73, v92
	v_mov_b32_e32 v70, v108
	s_and_b64 vcc, exec, s[40:41]
	v_mov_b32_e32 v71, v76
	s_cbranch_vccnz .LBB0_355
	v_bfe_u32 v66, v84, 6, 5
	v_and_b32_e32 v67, 62, v84
	v_cndmask_b32_e64 v66, v67, v66, s[36:37]
	v_lshlrev_b32_e32 v66, 6, v66
	v_add_u32_e32 v67, v220, v66
	v_add_u32_e32 v66, v221, v66
	v_and_b32_e32 v68, 64, v213
	ds_read_b128 v[86:89], v66
	v_xor_b32_e32 v66, 4, v213
	v_add_u32_e32 v68, 64, v68
	v_cmp_lt_i32_e32 vcc, v66, v68
	s_nop 1
	v_cndmask_b32_e32 v66, v213, v66, vcc
	v_lshlrev_b32_e32 v66, 2, v66
	ds_bpermute_b32 v74, v66, v124
	ds_bpermute_b32 v75, v66, v92
	ds_bpermute_b32 v82, v66, v108
	ds_bpermute_b32 v83, v66, v76
	ds_read_b128 v[66:69], v67 offset:57344
	s_waitcnt lgkmcnt(3)
	v_pk_mul_f32 v[74:75], v[86:87], v[74:75]
	s_waitcnt lgkmcnt(1)
	v_pk_mul_f32 v[82:83], v[88:89], v[82:83]
	s_and_saveexec_b64 s[50:51], s[38:39]
	s_xor_b64 s[50:51], exec, s[50:51]
	s_cbranch_execz .LBB0_352
	s_waitcnt lgkmcnt(0)
	v_pk_fma_f32 v[72:73], v[72:73], v[66:67], v[74:75]
	v_pk_fma_f32 v[70:71], v[70:71], v[68:69], v[82:83]

.LBB0_365:
	v_add_u32_e32 v74, 19, v222
	v_mov_b32_e32 v92, v125
	s_and_b64 vcc, exec, s[40:41]
	v_mov_b32_e32 v76, v109
	s_cbranch_vccnz .LBB0_371
	v_bfe_u32 v66, v74, 6, 5
	v_and_b32_e32 v67, 63, v74
	v_cndmask_b32_e64 v66, v67, v66, s[36:37]
	v_lshlrev_b32_e32 v66, 6, v66
	v_add_u32_e32 v67, v220, v66
	v_add_u32_e32 v66, v221, v66
	v_and_b32_e32 v68, 64, v213
	ds_read_b128 v[70:73], v66
	v_xor_b32_e32 v66, 4, v213
	v_add_u32_e32 v68, 64, v68
	v_cmp_lt_i32_e32 vcc, v66, v68
	s_nop 1
	v_cndmask_b32_e32 v66, v213, v66, vcc
	v_lshlrev_b32_e32 v66, 2, v66
	ds_bpermute_b32 v82, v66, v125
	ds_bpermute_b32 v83, v66, v93
	ds_bpermute_b32 v84, v66, v109
	ds_bpermute_b32 v85, v66, v77
	ds_read_b128 v[66:69], v67 offset:57344
	s_waitcnt lgkmcnt(3)
	v_pk_mul_f32 v[70:71], v[70:71], v[82:83]
	s_waitcnt lgkmcnt(1)
	v_pk_mul_f32 v[72:73], v[72:73], v[84:85]
	s_and_saveexec_b64 s[50:51], s[38:39]
	s_xor_b64 s[50:51], exec, s[50:51]
	s_cbranch_execz .LBB0_368
	s_waitcnt lgkmcnt(0)
	v_pk_fma_f32 v[92:93], v[92:93], v[66:67], v[70:71]
	v_pk_fma_f32 v[76:77], v[76:77], v[68:69], v[72:73]

.LBB0_381:
	v_add_u32_e32 v82, 24, v222
	v_mov_b32_e32 v72, v126
	v_mov_b32_e32 v73, v94
	v_mov_b32_e32 v70, v110
	s_and_b64 vcc, exec, s[40:41]
	v_mov_b32_e32 v71, v78
	s_cbranch_vccnz .LBB0_387
	v_bfe_u32 v66, v82, 6, 5
	v_and_b32_e32 v67, 60, v82
	v_cndmask_b32_e64 v66, v67, v66, s[36:37]
	v_lshlrev_b32_e32 v66, 6, v66
	v_add_u32_e32 v67, v220, v66
	v_add_u32_e32 v66, v221, v66
	v_and_b32_e32 v68, 64, v213
	ds_read_b128 v[74:77], v66
	v_xor_b32_e32 v66, 4, v213
	v_add_u32_e32 v68, 64, v68
	v_cmp_lt_i32_e32 vcc, v66, v68
	s_nop 1
	v_cndmask_b32_e32 v66, v213, v66, vcc
	v_lshlrev_b32_e32 v66, 2, v66
	ds_bpermute_b32 v84, v66, v126
	ds_bpermute_b32 v85, v66, v94
	ds_bpermute_b32 v86, v66, v110
	ds_bpermute_b32 v87, v66, v78
	ds_read_b128 v[66:69], v67 offset:57344
	s_waitcnt lgkmcnt(3)
	v_pk_mul_f32 v[74:75], v[74:75], v[84:85]
	s_waitcnt lgkmcnt(1)
	v_pk_mul_f32 v[76:77], v[76:77], v[86:87]
	s_and_saveexec_b64 s[50:51], s[38:39]
	s_xor_b64 s[50:51], exec, s[50:51]
	s_cbranch_execz .LBB0_384
	s_waitcnt lgkmcnt(0)
	v_pk_fma_f32 v[72:73], v[72:73], v[66:67], v[74:75]
	v_pk_fma_f32 v[70:71], v[70:71], v[68:69], v[76:77]

.LBB0_397:
	v_add_u32_e32 v74, 25, v222
	v_mov_b32_e32 v94, v127
	s_and_b64 vcc, exec, s[40:41]
	v_mov_b32_e32 v78, v111
	s_cbranch_vccnz .LBB0_403
	v_bfe_u32 v66, v74, 6, 5
	v_and_b32_e32 v67, 61, v74
	v_cndmask_b32_e64 v66, v67, v66, s[36:37]
	v_lshlrev_b32_e32 v66, 6, v66
	v_add_u32_e32 v67, v220, v66
	v_add_u32_e32 v66, v221, v66
	v_and_b32_e32 v68, 64, v213
	ds_read_b128 v[70:73], v66
	v_xor_b32_e32 v66, 4, v213
	v_add_u32_e32 v68, 64, v68
	v_cmp_lt_i32_e32 vcc, v66, v68
	s_nop 1
	v_cndmask_b32_e32 v66, v213, v66, vcc
	v_lshlrev_b32_e32 v66, 2, v66
	ds_bpermute_b32 v76, v66, v127
	ds_bpermute_b32 v77, v66, v95
	ds_bpermute_b32 v82, v66, v111
	ds_bpermute_b32 v83, v66, v79
	ds_read_b128 v[66:69], v67 offset:57344
	s_waitcnt lgkmcnt(3)
	v_pk_mul_f32 v[70:71], v[70:71], v[76:77]
	s_waitcnt lgkmcnt(1)
	v_pk_mul_f32 v[72:73], v[72:73], v[82:83]
	s_and_saveexec_b64 s[50:51], s[38:39]
	s_xor_b64 s[50:51], exec, s[50:51]
	s_cbranch_execz .LBB0_400
	s_waitcnt lgkmcnt(0)
	v_pk_fma_f32 v[94:95], v[94:95], v[66:67], v[70:71]
	v_pk_fma_f32 v[78:79], v[78:79], v[68:69], v[72:73]

.LBB0_413:
	v_add_u32_e32 v78, 26, v222
	v_mov_b32_e32 v72, v128
	v_mov_b32_e32 v73, v96
	v_mov_b32_e32 v70, v112
	s_and_b64 vcc, exec, s[40:41]
	v_mov_b32_e32 v71, v80
	s_cbranch_vccnz .LBB0_419
	v_bfe_u32 v66, v78, 6, 5
	v_and_b32_e32 v67, 62, v78
	v_cndmask_b32_e64 v66, v67, v66, s[36:37]
	v_lshlrev_b32_e32 v66, 6, v66
	v_add_u32_e32 v67, v220, v66
	v_add_u32_e32 v66, v221, v66
	v_and_b32_e32 v68, 64, v213
	ds_read_b128 v[74:77], v66
	v_xor_b32_e32 v66, 4, v213
	v_add_u32_e32 v68, 64, v68
	v_cmp_lt_i32_e32 vcc, v66, v68
	s_nop 1
	v_cndmask_b32_e32 v66, v213, v66, vcc
	v_lshlrev_b32_e32 v66, 2, v66
	ds_bpermute_b32 v82, v66, v128
	ds_bpermute_b32 v83, v66, v96
	ds_bpermute_b32 v84, v66, v112
	ds_bpermute_b32 v85, v66, v80
	ds_read_b128 v[66:69], v67 offset:57344
	s_waitcnt lgkmcnt(3)
	v_pk_mul_f32 v[74:75], v[74:75], v[82:83]
	s_waitcnt lgkmcnt(1)
	v_pk_mul_f32 v[76:77], v[76:77], v[84:85]
	s_and_saveexec_b64 s[50:51], s[38:39]
	s_xor_b64 s[50:51], exec, s[50:51]
	s_cbranch_execz .LBB0_416
	s_waitcnt lgkmcnt(0)
	v_pk_fma_f32 v[72:73], v[72:73], v[66:67], v[74:75]
	v_pk_fma_f32 v[70:71], v[70:71], v[68:69], v[76:77]

.LBB0_429:
	v_add_u32_e32 v74, 27, v222
	v_mov_b32_e32 v96, v129
	s_and_b64 vcc, exec, s[40:41]
	v_mov_b32_e32 v80, v113
	s_cbranch_vccnz .LBB0_435
	v_bfe_u32 v66, v74, 6, 5
	v_and_b32_e32 v67, 63, v74
	v_cndmask_b32_e64 v66, v67, v66, s[36:37]
	v_lshlrev_b32_e32 v66, 6, v66
	v_add_u32_e32 v67, v220, v66
	v_add_u32_e32 v66, v221, v66
	v_and_b32_e32 v68, 64, v213
	ds_read_b128 v[70:73], v66
	v_xor_b32_e32 v66, 4, v213
	v_add_u32_e32 v68, 64, v68
	v_cmp_lt_i32_e32 vcc, v66, v68
	s_nop 1
	v_cndmask_b32_e32 v66, v213, v66, vcc
	v_lshlrev_b32_e32 v66, 2, v66
	ds_bpermute_b32 v76, v66, v129
	ds_bpermute_b32 v77, v66, v97
	ds_bpermute_b32 v78, v66, v113
	ds_bpermute_b32 v79, v66, v81
	ds_read_b128 v[66:69], v67 offset:57344
	s_waitcnt lgkmcnt(3)
	v_pk_mul_f32 v[70:71], v[70:71], v[76:77]
	s_waitcnt lgkmcnt(1)
	v_pk_mul_f32 v[72:73], v[72:73], v[78:79]
	s_and_saveexec_b64 s[50:51], s[38:39]
	s_xor_b64 s[50:51], exec, s[50:51]
	s_cbranch_execz .LBB0_432
	s_waitcnt lgkmcnt(0)
	v_pk_fma_f32 v[96:97], v[96:97], v[66:67], v[70:71]
	v_pk_fma_f32 v[80:81], v[80:81], v[68:69], v[72:73]

.LBB0_445:
	v_add_u32_e32 v78, 32, v222
	v_mov_b32_e32 v72, v50
	v_mov_b32_e32 v73, v18
	v_mov_b32_e32 v70, v34
	v_mov_b32_e32 v71, v2
	s_and_b64 vcc, exec, s[40:41]
	v_bfe_u32 v79, v78, 6, 5
	s_cbranch_vccnz .LBB0_451
	v_and_b32_e32 v66, 60, v78
	v_cndmask_b32_e64 v66, v66, v79, s[36:37]
	v_lshlrev_b32_e32 v66, 6, v66
	v_add_u32_e32 v67, v220, v66
	v_add_u32_e32 v66, v221, v66
	v_and_b32_e32 v68, 64, v213
	ds_read_b128 v[74:77], v66
	v_xor_b32_e32 v66, 4, v213
	v_add_u32_e32 v68, 64, v68
	v_cmp_lt_i32_e32 vcc, v66, v68
	s_nop 1
	v_cndmask_b32_e32 v66, v213, v66, vcc
	v_lshlrev_b32_e32 v66, 2, v66
	ds_bpermute_b32 v80, v66, v50
	ds_bpermute_b32 v81, v66, v18
	ds_bpermute_b32 v82, v66, v34
	ds_bpermute_b32 v83, v66, v2
	ds_read_b128 v[66:69], v67 offset:57344
	s_waitcnt lgkmcnt(3)
	v_pk_mul_f32 v[74:75], v[74:75], v[80:81]
	s_waitcnt lgkmcnt(1)
	v_pk_mul_f32 v[76:77], v[76:77], v[82:83]
	s_and_saveexec_b64 s[50:51], s[38:39]
	s_xor_b64 s[50:51], exec, s[50:51]
	s_cbranch_execz .LBB0_448
	s_waitcnt lgkmcnt(0)
	v_pk_fma_f32 v[72:73], v[72:73], v[66:67], v[74:75]
	v_pk_fma_f32 v[70:71], v[70:71], v[68:69], v[76:77]

.LBB0_461:
	v_or_b32_e32 v70, 1, v78
	v_mov_b32_e32 v18, v51
	s_and_b64 vcc, exec, s[40:41]
	v_mov_b32_e32 v2, v35
	s_cbranch_vccnz .LBB0_467
	v_and_b32_e32 v34, 61, v70
	v_cndmask_b32_e64 v34, v34, v79, s[36:37]
	v_lshlrev_b32_e32 v34, 6, v34
	v_add_u32_e32 v66, v220, v34
	v_add_u32_e32 v34, v221, v34
	v_and_b32_e32 v50, 64, v213
	ds_read_b128 v[72:75], v34
	ds_read_b128 v[66:69], v66 offset:57344
	v_xor_b32_e32 v34, 4, v213
	v_add_u32_e32 v50, 64, v50
	v_cmp_lt_i32_e32 vcc, v34, v50
	s_nop 1
	v_cndmask_b32_e32 v34, v213, v34, vcc
	v_lshlrev_b32_e32 v34, 2, v34
	ds_bpermute_b32 v50, v34, v51
	ds_bpermute_b32 v51, v34, v19
	ds_bpermute_b32 v76, v34, v35
	ds_bpermute_b32 v77, v34, v3
	s_waitcnt lgkmcnt(2)
	v_pk_mul_f32 v[34:35], v[72:73], v[50:51]
	s_waitcnt lgkmcnt(0)
	v_pk_mul_f32 v[50:51], v[74:75], v[76:77]
	s_and_saveexec_b64 s[50:51], s[38:39]
	s_xor_b64 s[50:51], exec, s[50:51]
	v_pk_fma_f32 v[18:19], v[18:19], v[66:67], v[34:35]
	v_pk_fma_f32 v[2:3], v[2:3], v[68:69], v[50:51]
	s_andn2_saveexec_b64 s[50:51], s[50:51]
	v_pk_fma_f32 v[18:19], v[18:19], v[66:67], v[34:35] neg_lo:[0,0,1] neg_hi:[0,0,1]
	v_pk_fma_f32 v[2:3], v[2:3], v[68:69], v[50:51] neg_lo:[0,0,1] neg_hi:[0,0,1]
	s_or_b64 exec, exec, s[50:51]

.LBB0_477:
	v_or_b32_e32 v70, 2, v78
	v_mov_b32_e32 v18, v52
	v_mov_b32_e32 v19, v20
	v_mov_b32_e32 v2, v36
	s_and_b64 vcc, exec, s[40:41]
	v_mov_b32_e32 v3, v4
	s_cbranch_vccnz .LBB0_483
	v_and_b32_e32 v34, 62, v70
	v_cndmask_b32_e64 v34, v34, v79, s[36:37]
	v_lshlrev_b32_e32 v34, 6, v34
	v_add_u32_e32 v66, v220, v34
	v_add_u32_e32 v34, v221, v34
	v_and_b32_e32 v35, 64, v213
	ds_read_b128 v[72:75], v34
	ds_read_b128 v[66:69], v66 offset:57344
	v_xor_b32_e32 v34, 4, v213
	v_add_u32_e32 v35, 64, v35
	v_cmp_lt_i32_e32 vcc, v34, v35
	s_nop 1
	v_cndmask_b32_e32 v34, v213, v34, vcc
	v_lshlrev_b32_e32 v51, 2, v34
	ds_bpermute_b32 v34, v51, v52
	ds_bpermute_b32 v35, v51, v20
	ds_bpermute_b32 v50, v51, v36
	ds_bpermute_b32 v51, v51, v4
	s_waitcnt lgkmcnt(2)
	v_pk_mul_f32 v[34:35], v[72:73], v[34:35]
	s_waitcnt lgkmcnt(0)
	v_pk_mul_f32 v[50:51], v[74:75], v[50:51]
	s_and_saveexec_b64 s[50:51], s[38:39]
	s_xor_b64 s[50:51], exec, s[50:51]
	v_pk_fma_f32 v[18:19], v[18:19], v[66:67], v[34:35]
	v_pk_fma_f32 v[2:3], v[2:3], v[68:69], v[50:51]
	s_andn2_saveexec_b64 s[50:51], s[50:51]
	v_pk_fma_f32 v[18:19], v[18:19], v[66:67], v[34:35] neg_lo:[0,0,1] neg_hi:[0,0,1]
	v_pk_fma_f32 v[2:3], v[2:3], v[68:69], v[50:51] neg_lo:[0,0,1] neg_hi:[0,0,1]
	s_or_b64 exec, exec, s[50:51]

.LBB0_493:
	v_or_b32_e32 v50, 3, v78
	v_mov_b32_e32 v20, v53
	s_and_b64 vcc, exec, s[40:41]
	v_mov_b32_e32 v4, v37
	s_cbranch_vccnz .LBB0_499
	v_and_b32_e32 v2, 63, v50
	v_cndmask_b32_e64 v2, v2, v79, s[36:37]
	v_lshlrev_b32_e32 v2, 6, v2
	v_add_u32_e32 v34, v220, v2
	v_add_u32_e32 v2, v221, v2
	v_and_b32_e32 v3, 64, v213
	ds_read_b128 v[66:69], v2
	v_xor_b32_e32 v2, 4, v213
	v_add_u32_e32 v3, 64, v3
	v_cmp_lt_i32_e32 vcc, v2, v3
	s_nop 1
	v_cndmask_b32_e32 v2, v213, v2, vcc
	v_lshlrev_b32_e32 v19, 2, v2
	ds_bpermute_b32 v2, v19, v53
	ds_bpermute_b32 v3, v19, v21
	ds_bpermute_b32 v18, v19, v37
	ds_bpermute_b32 v19, v19, v5
	ds_read_b128 v[34:37], v34 offset:57344
	s_waitcnt lgkmcnt(3)
	v_pk_mul_f32 v[2:3], v[66:67], v[2:3]
	s_waitcnt lgkmcnt(1)
	v_pk_mul_f32 v[18:19], v[68:69], v[18:19]
	s_and_saveexec_b64 s[50:51], s[38:39]
	s_xor_b64 s[50:51], exec, s[50:51]
	s_cbranch_execz .LBB0_496
	s_waitcnt lgkmcnt(0)
	v_pk_fma_f32 v[20:21], v[20:21], v[34:35], v[2:3]
	v_pk_fma_f32 v[4:5], v[4:5], v[36:37], v[18:19]

.LBB0_509:
	v_add_u32_e32 v50, 40, v222
	v_mov_b32_e32 v20, v54
	v_mov_b32_e32 v21, v22
	v_mov_b32_e32 v18, v38
	s_and_b64 vcc, exec, s[40:41]
	v_mov_b32_e32 v19, v6
	s_cbranch_vccnz .LBB0_515
	v_bfe_u32 v2, v50, 6, 5
	v_and_b32_e32 v3, 60, v50
	v_cndmask_b32_e64 v2, v3, v2, s[36:37]
	v_lshlrev_b32_e32 v2, 6, v2
	v_add_u32_e32 v3, v220, v2
	v_add_u32_e32 v2, v221, v2
	v_and_b32_e32 v4, 64, v213
	s_waitcnt lgkmcnt(0)
	ds_read_b128 v[34:37], v2
	v_xor_b32_e32 v2, 4, v213
	v_add_u32_e32 v4, 64, v4
	v_cmp_lt_i32_e32 vcc, v2, v4
	s_nop 1
	v_cndmask_b32_e32 v2, v213, v2, vcc
	v_lshlrev_b32_e32 v2, 2, v2
	ds_bpermute_b32 v52, v2, v54
	ds_bpermute_b32 v53, v2, v22
	ds_bpermute_b32 v66, v2, v38
	ds_bpermute_b32 v67, v2, v6
	ds_read_b128 v[2:5], v3 offset:57344
	s_waitcnt lgkmcnt(3)
	v_pk_mul_f32 v[34:35], v[34:35], v[52:53]
	s_waitcnt lgkmcnt(1)
	v_pk_mul_f32 v[36:37], v[36:37], v[66:67]
	s_and_saveexec_b64 s[50:51], s[38:39]
	s_xor_b64 s[50:51], exec, s[50:51]
	s_cbranch_execz .LBB0_512
	s_waitcnt lgkmcnt(0)
	v_pk_fma_f32 v[20:21], v[20:21], v[2:3], v[34:35]
	v_pk_fma_f32 v[18:19], v[18:19], v[4:5], v[36:37]

.LBB0_525:
	v_add_u32_e32 v34, 41, v222
	v_mov_b32_e32 v22, v55
	s_and_b64 vcc, exec, s[40:41]
	v_mov_b32_e32 v6, v39
	s_cbranch_vccnz .LBB0_531
	v_bfe_u32 v2, v34, 6, 5
	v_and_b32_e32 v3, 61, v34
	v_cndmask_b32_e64 v2, v3, v2, s[36:37]
	v_lshlrev_b32_e32 v2, 6, v2
	v_add_u32_e32 v3, v220, v2
	v_add_u32_e32 v2, v221, v2
	v_and_b32_e32 v4, 64, v213
	ds_read_b128 v[18:21], v2
	v_xor_b32_e32 v2, 4, v213
	v_add_u32_e32 v4, 64, v4
	v_cmp_lt_i32_e32 vcc, v2, v4
	s_nop 1
	v_cndmask_b32_e32 v2, v213, v2, vcc
	v_lshlrev_b32_e32 v2, 2, v2
	ds_bpermute_b32 v36, v2, v55
	ds_bpermute_b32 v37, v2, v23
	ds_bpermute_b32 v38, v2, v39
	ds_bpermute_b32 v39, v2, v7
	ds_read_b128 v[2:5], v3 offset:57344
	s_waitcnt lgkmcnt(3)
	v_pk_mul_f32 v[18:19], v[18:19], v[36:37]
	s_waitcnt lgkmcnt(1)
	v_pk_mul_f32 v[20:21], v[20:21], v[38:39]
	s_and_saveexec_b64 s[50:51], s[38:39]
	s_xor_b64 s[50:51], exec, s[50:51]
	s_cbranch_execz .LBB0_528
	s_waitcnt lgkmcnt(0)
	v_pk_fma_f32 v[22:23], v[22:23], v[2:3], v[18:19]
	v_pk_fma_f32 v[6:7], v[6:7], v[4:5], v[20:21]

.LBB0_541:
	v_add_u32_e32 v34, 42, v222
	v_mov_b32_e32 v18, v56
	v_mov_b32_e32 v19, v24
	v_mov_b32_e32 v6, v40
	s_and_b64 vcc, exec, s[40:41]
	v_mov_b32_e32 v7, v8
	s_cbranch_vccnz .LBB0_547
	v_bfe_u32 v2, v34, 6, 5
	v_and_b32_e32 v3, 62, v34
	v_cndmask_b32_e64 v2, v3, v2, s[36:37]
	v_lshlrev_b32_e32 v2, 6, v2
	v_add_u32_e32 v3, v220, v2
	v_add_u32_e32 v2, v221, v2
	v_and_b32_e32 v4, 64, v213
	ds_read_b128 v[20:23], v2
	v_xor_b32_e32 v2, 4, v213
	v_add_u32_e32 v4, 64, v4
	v_cmp_lt_i32_e32 vcc, v2, v4
	s_nop 1
	v_cndmask_b32_e32 v2, v213, v2, vcc
	v_lshlrev_b32_e32 v2, 2, v2
	ds_bpermute_b32 v36, v2, v56
	ds_bpermute_b32 v37, v2, v24
	ds_bpermute_b32 v38, v2, v40
	ds_bpermute_b32 v39, v2, v8
	ds_read_b128 v[2:5], v3 offset:57344
	s_waitcnt lgkmcnt(3)
	v_pk_mul_f32 v[20:21], v[20:21], v[36:37]
	s_waitcnt lgkmcnt(1)
	v_pk_mul_f32 v[22:23], v[22:23], v[38:39]
	s_and_saveexec_b64 s[50:51], s[38:39]
	s_xor_b64 s[50:51], exec, s[50:51]
	s_cbranch_execz .LBB0_544
	s_waitcnt lgkmcnt(0)
	v_pk_fma_f32 v[18:19], v[18:19], v[2:3], v[20:21]
	v_pk_fma_f32 v[6:7], v[6:7], v[4:5], v[22:23]

.LBB0_557:
	v_add_u32_e32 v20, 43, v222
	v_mov_b32_e32 v24, v57
	s_and_b64 vcc, exec, s[40:41]
	v_mov_b32_e32 v8, v41
	s_cbranch_vccnz .LBB0_563
	v_bfe_u32 v2, v20, 6, 5
	v_and_b32_e32 v3, 63, v20
	v_cndmask_b32_e64 v2, v3, v2, s[36:37]
	v_lshlrev_b32_e32 v2, 6, v2
	v_add_u32_e32 v3, v220, v2
	v_add_u32_e32 v2, v221, v2
	v_and_b32_e32 v4, 64, v213
	ds_read_b128 v[34:37], v2
	v_xor_b32_e32 v2, 4, v213
	v_add_u32_e32 v4, 64, v4
	v_cmp_lt_i32_e32 vcc, v2, v4
	s_nop 1
	v_cndmask_b32_e32 v2, v213, v2, vcc
	v_lshlrev_b32_e32 v2, 2, v2
	ds_bpermute_b32 v6, v2, v57
	ds_bpermute_b32 v7, v2, v25
	ds_bpermute_b32 v18, v2, v41
	ds_bpermute_b32 v19, v2, v9
	ds_read_b128 v[2:5], v3 offset:57344
	s_waitcnt lgkmcnt(3)
	v_pk_mul_f32 v[6:7], v[34:35], v[6:7]
	s_waitcnt lgkmcnt(1)
	v_pk_mul_f32 v[18:19], v[36:37], v[18:19]
	s_and_saveexec_b64 s[50:51], s[38:39]
	s_xor_b64 s[50:51], exec, s[50:51]
	s_cbranch_execz .LBB0_560
	s_waitcnt lgkmcnt(0)
	v_pk_fma_f32 v[24:25], v[24:25], v[2:3], v[6:7]
	v_pk_fma_f32 v[8:9], v[8:9], v[4:5], v[18:19]

.LBB0_573:
	v_add_u32_e32 v22, 48, v222
	v_mov_b32_e32 v8, v58
	v_mov_b32_e32 v9, v26
	v_mov_b32_e32 v6, v42
	s_and_b64 vcc, exec, s[40:41]
	v_mov_b32_e32 v7, v10
	s_cbranch_vccnz .LBB0_579
	v_bfe_u32 v2, v22, 6, 5
	v_and_b32_e32 v3, 60, v22
	v_cndmask_b32_e64 v2, v3, v2, s[36:37]
	v_lshlrev_b32_e32 v2, 6, v2
	v_add_u32_e32 v3, v220, v2
	v_add_u32_e32 v2, v221, v2
	v_and_b32_e32 v4, 64, v213
	ds_read_b128 v[18:21], v2
	v_xor_b32_e32 v2, 4, v213
	v_add_u32_e32 v4, 64, v4
	v_cmp_lt_i32_e32 vcc, v2, v4
	s_nop 1
	v_cndmask_b32_e32 v2, v213, v2, vcc
	v_lshlrev_b32_e32 v2, 2, v2
	ds_bpermute_b32 v24, v2, v58
	ds_bpermute_b32 v25, v2, v26
	ds_bpermute_b32 v34, v2, v42
	ds_bpermute_b32 v35, v2, v10
	ds_read_b128 v[2:5], v3 offset:57344
	s_waitcnt lgkmcnt(3)
	v_pk_mul_f32 v[18:19], v[18:19], v[24:25]
	s_waitcnt lgkmcnt(1)
	v_pk_mul_f32 v[20:21], v[20:21], v[34:35]
	s_and_saveexec_b64 s[50:51], s[38:39]
	s_xor_b64 s[50:51], exec, s[50:51]
	s_cbranch_execz .LBB0_576
	s_waitcnt lgkmcnt(0)
	v_pk_fma_f32 v[8:9], v[8:9], v[2:3], v[18:19]
	v_pk_fma_f32 v[6:7], v[6:7], v[4:5], v[20:21]

.LBB0_589:
	v_add_u32_e32 v18, 49, v222
	v_mov_b32_e32 v26, v59
	s_and_b64 vcc, exec, s[40:41]
	v_mov_b32_e32 v10, v43
	s_cbranch_vccnz .LBB0_595
	v_bfe_u32 v2, v18, 6, 5
	v_and_b32_e32 v3, 61, v18
	v_cndmask_b32_e64 v2, v3, v2, s[36:37]
	v_lshlrev_b32_e32 v2, 6, v2
	v_add_u32_e32 v3, v220, v2
	v_add_u32_e32 v2, v221, v2
	v_and_b32_e32 v4, 64, v213
	ds_read_b128 v[6:9], v2
	v_xor_b32_e32 v2, 4, v213
	v_add_u32_e32 v4, 64, v4
	v_cmp_lt_i32_e32 vcc, v2, v4
	s_nop 1
	v_cndmask_b32_e32 v2, v213, v2, vcc
	v_lshlrev_b32_e32 v2, 2, v2
	ds_bpermute_b32 v20, v2, v59
	ds_bpermute_b32 v21, v2, v27
	ds_bpermute_b32 v22, v2, v43
	ds_bpermute_b32 v23, v2, v11
	ds_read_b128 v[2:5], v3 offset:57344
	s_waitcnt lgkmcnt(3)
	v_pk_mul_f32 v[6:7], v[6:7], v[20:21]
	s_waitcnt lgkmcnt(1)
	v_pk_mul_f32 v[8:9], v[8:9], v[22:23]
	s_and_saveexec_b64 s[50:51], s[38:39]
	s_xor_b64 s[50:51], exec, s[50:51]
	s_cbranch_execz .LBB0_592
	s_waitcnt lgkmcnt(0)
	v_pk_fma_f32 v[26:27], v[26:27], v[2:3], v[6:7]
	v_pk_fma_f32 v[10:11], v[10:11], v[4:5], v[8:9]

.LBB0_605:
	v_add_u32_e32 v20, 50, v222
	v_mov_b32_e32 v8, v60
	v_mov_b32_e32 v9, v28
	v_mov_b32_e32 v6, v44
	s_and_b64 vcc, exec, s[40:41]
	v_mov_b32_e32 v7, v12
	s_cbranch_vccnz .LBB0_611
	v_bfe_u32 v2, v20, 6, 5
	v_and_b32_e32 v3, 62, v20
	v_cndmask_b32_e64 v2, v3, v2, s[36:37]
	v_lshlrev_b32_e32 v2, 6, v2
	v_add_u32_e32 v3, v220, v2
	v_add_u32_e32 v2, v221, v2
	v_and_b32_e32 v4, 64, v213
	ds_read_b128 v[22:25], v2
	v_xor_b32_e32 v2, 4, v213
	v_add_u32_e32 v4, 64, v4
	v_cmp_lt_i32_e32 vcc, v2, v4
	s_nop 1
	v_cndmask_b32_e32 v2, v213, v2, vcc
	v_lshlrev_b32_e32 v2, 2, v2
	ds_bpermute_b32 v10, v2, v60
	ds_bpermute_b32 v11, v2, v28
	ds_bpermute_b32 v18, v2, v44
	ds_bpermute_b32 v19, v2, v12
	ds_read_b128 v[2:5], v3 offset:57344
	s_waitcnt lgkmcnt(3)
	v_pk_mul_f32 v[10:11], v[22:23], v[10:11]
	s_waitcnt lgkmcnt(1)
	v_pk_mul_f32 v[18:19], v[24:25], v[18:19]
	s_and_saveexec_b64 s[50:51], s[38:39]
	s_xor_b64 s[50:51], exec, s[50:51]
	s_cbranch_execz .LBB0_608
	s_waitcnt lgkmcnt(0)
	v_pk_fma_f32 v[8:9], v[8:9], v[2:3], v[10:11]
	v_pk_fma_f32 v[6:7], v[6:7], v[4:5], v[18:19]

.LBB0_621:
	v_add_u32_e32 v10, 51, v222
	v_mov_b32_e32 v28, v61
	s_and_b64 vcc, exec, s[40:41]
	v_mov_b32_e32 v12, v45
	s_cbranch_vccnz .LBB0_627
	v_bfe_u32 v2, v10, 6, 5
	v_and_b32_e32 v3, 63, v10
	v_cndmask_b32_e64 v2, v3, v2, s[36:37]
	v_lshlrev_b32_e32 v2, 6, v2
	v_add_u32_e32 v3, v220, v2
	v_add_u32_e32 v2, v221, v2
	v_and_b32_e32 v4, 64, v213
	ds_read_b128 v[6:9], v2
	v_xor_b32_e32 v2, 4, v213
	v_add_u32_e32 v4, 64, v4
	v_cmp_lt_i32_e32 vcc, v2, v4
	s_nop 1
	v_cndmask_b32_e32 v2, v213, v2, vcc
	v_lshlrev_b32_e32 v2, 2, v2
	ds_bpermute_b32 v18, v2, v61
	ds_bpermute_b32 v19, v2, v29
	ds_bpermute_b32 v20, v2, v45
	ds_bpermute_b32 v21, v2, v13
	ds_read_b128 v[2:5], v3 offset:57344
	s_waitcnt lgkmcnt(3)
	v_pk_mul_f32 v[6:7], v[6:7], v[18:19]
	s_waitcnt lgkmcnt(1)
	v_pk_mul_f32 v[8:9], v[8:9], v[20:21]
	s_and_saveexec_b64 s[50:51], s[38:39]
	s_xor_b64 s[50:51], exec, s[50:51]
	s_cbranch_execz .LBB0_624
	s_waitcnt lgkmcnt(0)
	v_pk_fma_f32 v[28:29], v[28:29], v[2:3], v[6:7]
	v_pk_fma_f32 v[12:13], v[12:13], v[4:5], v[8:9]

.LBB0_637:
	v_add_u32_e32 v18, 56, v222
	v_mov_b32_e32 v8, v62
	v_mov_b32_e32 v9, v30
	v_mov_b32_e32 v6, v46
	s_and_b64 vcc, exec, s[40:41]
	v_mov_b32_e32 v7, v14
	s_cbranch_vccnz .LBB0_643
	v_bfe_u32 v2, v18, 6, 5
	v_and_b32_e32 v3, 60, v18
	v_cndmask_b32_e64 v2, v3, v2, s[36:37]
	v_lshlrev_b32_e32 v2, 6, v2
	v_add_u32_e32 v3, v220, v2
	v_add_u32_e32 v2, v221, v2
	v_and_b32_e32 v4, 64, v213
	ds_read_b128 v[10:13], v2
	v_xor_b32_e32 v2, 4, v213
	v_add_u32_e32 v4, 64, v4
	v_cmp_lt_i32_e32 vcc, v2, v4
	s_nop 1
	v_cndmask_b32_e32 v2, v213, v2, vcc
	v_lshlrev_b32_e32 v2, 2, v2
	ds_bpermute_b32 v20, v2, v62
	ds_bpermute_b32 v21, v2, v30
	ds_bpermute_b32 v22, v2, v46
	ds_bpermute_b32 v23, v2, v14
	ds_read_b128 v[2:5], v3 offset:57344
	s_waitcnt lgkmcnt(3)
	v_pk_mul_f32 v[10:11], v[10:11], v[20:21]
	s_waitcnt lgkmcnt(1)
	v_pk_mul_f32 v[12:13], v[12:13], v[22:23]
	s_and_saveexec_b64 s[50:51], s[38:39]
	s_xor_b64 s[50:51], exec, s[50:51]
	s_cbranch_execz .LBB0_640
	s_waitcnt lgkmcnt(0)
	v_pk_fma_f32 v[8:9], v[8:9], v[2:3], v[10:11]
	v_pk_fma_f32 v[6:7], v[6:7], v[4:5], v[12:13]

.LBB0_653:
	v_add_u32_e32 v10, 57, v222
	v_mov_b32_e32 v30, v63
	s_and_b64 vcc, exec, s[40:41]
	v_mov_b32_e32 v14, v47
	s_cbranch_vccnz .LBB0_659
	v_bfe_u32 v2, v10, 6, 5
	v_and_b32_e32 v3, 61, v10
	v_cndmask_b32_e64 v2, v3, v2, s[36:37]
	v_lshlrev_b32_e32 v2, 6, v2
	v_add_u32_e32 v3, v220, v2
	v_add_u32_e32 v2, v221, v2
	v_and_b32_e32 v4, 64, v213
	ds_read_b128 v[6:9], v2
	v_xor_b32_e32 v2, 4, v213
	v_add_u32_e32 v4, 64, v4
	v_cmp_lt_i32_e32 vcc, v2, v4
	s_nop 1
	v_cndmask_b32_e32 v2, v213, v2, vcc
	v_lshlrev_b32_e32 v2, 2, v2
	ds_bpermute_b32 v12, v2, v63
	ds_bpermute_b32 v13, v2, v31
	ds_bpermute_b32 v18, v2, v47
	ds_bpermute_b32 v19, v2, v15
	ds_read_b128 v[2:5], v3 offset:57344
	s_waitcnt lgkmcnt(3)
	v_pk_mul_f32 v[6:7], v[6:7], v[12:13]
	s_waitcnt lgkmcnt(1)
	v_pk_mul_f32 v[8:9], v[8:9], v[18:19]
	s_and_saveexec_b64 s[50:51], s[38:39]
	s_xor_b64 s[50:51], exec, s[50:51]
	s_cbranch_execz .LBB0_656
	s_waitcnt lgkmcnt(0)
	v_pk_fma_f32 v[30:31], v[30:31], v[2:3], v[6:7]
	v_pk_fma_f32 v[14:15], v[14:15], v[4:5], v[8:9]

.LBB0_669:
	v_add_u32_e32 v14, 58, v222
	v_mov_b32_e32 v8, v64
	v_mov_b32_e32 v9, v32
	v_mov_b32_e32 v6, v48
	s_and_b64 vcc, exec, s[40:41]
	v_mov_b32_e32 v7, v16
	s_cbranch_vccnz .LBB0_675
	v_bfe_u32 v2, v14, 6, 5
	v_and_b32_e32 v3, 62, v14
	v_cndmask_b32_e64 v2, v3, v2, s[36:37]
	v_lshlrev_b32_e32 v2, 6, v2
	v_add_u32_e32 v3, v220, v2
	v_add_u32_e32 v2, v221, v2
	v_and_b32_e32 v4, 64, v213
	ds_read_b128 v[10:13], v2
	v_xor_b32_e32 v2, 4, v213
	v_add_u32_e32 v4, 64, v4
	v_cmp_lt_i32_e32 vcc, v2, v4
	s_nop 1
	v_cndmask_b32_e32 v2, v213, v2, vcc
	v_lshlrev_b32_e32 v2, 2, v2
	ds_bpermute_b32 v18, v2, v64
	ds_bpermute_b32 v19, v2, v32
	ds_bpermute_b32 v20, v2, v48
	ds_bpermute_b32 v21, v2, v16
	ds_read_b128 v[2:5], v3 offset:57344
	s_waitcnt lgkmcnt(3)
	v_pk_mul_f32 v[10:11], v[10:11], v[18:19]
	s_waitcnt lgkmcnt(1)
	v_pk_mul_f32 v[12:13], v[12:13], v[20:21]
	s_and_saveexec_b64 s[50:51], s[38:39]
	s_xor_b64 s[50:51], exec, s[50:51]
	s_cbranch_execz .LBB0_672
	s_waitcnt lgkmcnt(0)
	v_pk_fma_f32 v[8:9], v[8:9], v[2:3], v[10:11]
	v_pk_fma_f32 v[6:7], v[6:7], v[4:5], v[12:13]

.LBB0_685:
	v_add_u32_e32 v10, 59, v222
	v_mov_b32_e32 v32, v65
	s_and_b64 vcc, exec, s[40:41]
	v_mov_b32_e32 v16, v49
	s_cbranch_vccnz .LBB0_691
	v_bfe_u32 v2, v10, 6, 5
	v_and_b32_e32 v3, 63, v10
	v_cndmask_b32_e64 v2, v3, v2, s[36:37]
	v_lshlrev_b32_e32 v2, 6, v2
	v_add_u32_e32 v3, v220, v2
	v_add_u32_e32 v2, v221, v2
	v_and_b32_e32 v4, 64, v213
	ds_read_b128 v[6:9], v2
	v_xor_b32_e32 v2, 4, v213
	v_add_u32_e32 v4, 64, v4
	v_cmp_lt_i32_e32 vcc, v2, v4
	s_nop 1
	v_cndmask_b32_e32 v2, v213, v2, vcc
	v_lshlrev_b32_e32 v2, 2, v2
	ds_bpermute_b32 v12, v2, v65
	ds_bpermute_b32 v13, v2, v33
	ds_bpermute_b32 v14, v2, v49
	ds_bpermute_b32 v15, v2, v17
	ds_read_b128 v[2:5], v3 offset:57344
	s_waitcnt lgkmcnt(3)
	v_pk_mul_f32 v[6:7], v[6:7], v[12:13]
	s_waitcnt lgkmcnt(1)
	v_pk_mul_f32 v[8:9], v[8:9], v[14:15]
	s_and_saveexec_b64 s[40:41], s[38:39]
	s_xor_b64 s[40:41], exec, s[40:41]
	s_cbranch_execz .LBB0_688
	s_waitcnt lgkmcnt(0)
	v_pk_fma_f32 v[32:33], v[32:33], v[2:3], v[6:7]
	v_pk_fma_f32 v[16:17], v[16:17], v[4:5], v[8:9]

.LBB0_1415:
	s_or_b64 exec, exec, s[4:5]
	s_movk_i32 s34, 0x60
	v_readlane_b32 s0, v245, 13
	s_barrier
	s_cmp_ge_i32 s0, s34
	s_cbranch_scc1 .LBB0_1426
	v_mov_b32_e32 v198, v187
	s_lshl_b32 s0, s85, 26
	v_readlane_b32 s50, v247, 47
	v_readlane_b32 s51, v247, 48
	s_add_u32 s35, s50, s0
	s_addc_u32 s36, s51, 0
	v_readlane_b32 s4, v245, 24
	v_readlane_b32 s5, v245, 25
	s_add_u32 s0, s35, s4
	s_addc_u32 s5, s36, s5
	v_readlane_b32 s4, v245, 23
	s_add_u32 s4, s0, s4
	s_addc_u32 s5, s5, 0
	v_readlane_b32 s6, v245, 26
	v_readlane_b32 s7, v245, 27
	v_readlane_b32 s39, v245, 16
	v_readlane_b32 s38, v245, 13
	s_mov_b32 s37, 1
	v_and_b32_e32 v3, 31, v198
	v_ashrrev_i32_e32 v9, 5, v198
	v_lshlrev_b32_e32 v2, 2, v3
	v_lshlrev_b32_e32 v0, 1, v2
	v_bfe_u32 v199, v198, 5, 1
	v_and_b32_e32 v203, 0xffffffc0, v198
	v_lshl_add_u32 v204, v198, 2, 0
	v_lshl_or_b32 v4, v9, 12, v2
	v_lshlrev_b32_e32 v181, 2, v4
	v_readfirstlane_b32 s75, v198
	s_and_b32 s75, s75, 0xc0
	s_lshl_b32 s75, s75, 8
	s_movk_i32 s76, 0x2000
	v_lshrrev_b32_e32 v5, 1, v3
	v_and_b32_e32 v5, 7, v5
	v_xor_b32_e32 v5, v5, v199
	v_lshlrev_b32_e32 v5, 4, v5
	v_lshl_or_b32 v5, v3, 7, v5
	v_or_b32_e32 v174, s75, v5
	v_xor_b32_e32 v175, 32, v174
	v_xor_b32_e32 v176, 64, v174
	v_xor_b32_e32 v177, 0x60, v174
	v_lshrrev_b32_e32 v5, 2, v3
	v_and_b32_e32 v5, 3, v5
	v_xor_b32_e32 v6, v5, v199
	v_lshlrev_b32_e32 v6, 4, v6
	v_lshl_or_b32 v6, v3, 6, v6
	v_add_u32_e32 v178, 0x10000, v6
	v_xor_b32_e32 v179, 32, v178
	v_lshrrev_b32_e32 v6, 1, v9
	v_xor_b32_e32 v6, v6, v5
	v_lshlrev_b32_e32 v6, 4, v6
	v_and_b32_e32 v7, 1, v9
	v_lshl_or_b32 v6, v7, 3, v6
	v_lshl_or_b32 v6, v3, 6, v6
	v_add_u32_e32 v180, 0x10000, v6
	v_and_b32_e32 v5, 7, v198
	v_bfe_u32 v6, v198, 4, 2
	v_xor_b32_e32 v5, v5, v6
	v_lshlrev_b32_e32 v200, 4, v5
	v_xor_b32_e32 v201, 64, v200
	s_add_u32 s70, s6, 0xfffff000
	s_addc_u32 s71, s7, -1
	v_lshrrev_b32_e32 v5, 3, v198
	v_and_b32_e32 v5, 7, v5
	v_and_b32_e32 v6, 0xc0, v198
	v_or_b32_e32 v5, v5, v6
	v_lshl_add_u32 v162, v5, 11, v200
	v_lshl_add_u32 v163, v5, 11, v201
	v_lshl_add_u32 v164, v5, 11, v200
	v_lshl_add_u32 v165, v5, 11, v201
	v_lshl_add_u32 v166, v5, 11, v200
	v_lshl_add_u32 v167, v5, 11, v201
	v_lshl_add_u32 v168, v5, 11, v200
	v_lshl_add_u32 v169, v5, 11, v201
	v_add_u32_e32 v162, 0x1000, v162
	v_add_u32_e32 v163, 0x4c00, v163
	v_add_u32_e32 v164, 0x8800, v164
	v_add_u32_e32 v165, 0xc400, v165
	v_add_u32_e32 v166, 0x11000, v166
	v_add_u32_e32 v167, 0x14c00, v167
	v_add_u32_e32 v168, 0x18800, v168
	v_add_u32_e32 v169, 0x1c400, v169
	s_lshl_b32 s0, s39, 1
	s_and_b32 s66, s0, 30
	s_lshl_b32 s66, s66, 6
	s_add_u32 s66, s70, s66
	s_addc_u32 s67, s71, 0
	s_mov_b32 m0, s75
	s_nop 0
	global_load_lds_dwordx4 v162, s[66:67]
	global_load_lds_dwordx4 v163, s[66:67] offset:1024
	global_load_lds_dwordx4 v164, s[66:67] offset:2048
	global_load_lds_dwordx4 v165, s[66:67] offset:3072
	s_add_u32 m0, m0, 0x1000
	s_nop 0
	global_load_lds_dwordx4 v166, s[66:67]
	global_load_lds_dwordx4 v167, s[66:67] offset:1024
	global_load_lds_dwordx4 v168, s[66:67] offset:2048
	global_load_lds_dwordx4 v169, s[66:67] offset:3072
	s_and_b32 s58, s0, 31
	s_lshl_b32 s58, s58, 17
	s_add_u32 s58, s4, s58
	s_addc_u32 s59, s5, 0
	s_add_u32 s60, s58, 0x1000
	s_addc_u32 s61, s59, 0
	s_add_u32 s62, s58, s33
	s_addc_u32 s63, s59, 0
	s_add_u32 s64, s58, 0x3000
	s_addc_u32 s65, s59, 0
	global_load_dwordx4 v[130:133], v181, s[58:59]
	global_load_dwordx4 v[134:137], v181, s[60:61]
	global_load_dwordx4 v[138:141], v181, s[62:63]
	global_load_dwordx4 v[142:145], v181, s[64:65]
	s_add_i32 s0, s0, 1
	s_and_b32 s58, s0, 31
	s_lshl_b32 s58, s58, 17
	s_add_u32 s58, s4, s58
	s_addc_u32 s59, s5, 0
	s_add_u32 s60, s58, 0x1000
	s_addc_u32 s61, s59, 0
	s_add_u32 s62, s58, s33
	s_addc_u32 s63, s59, 0
	s_add_u32 s64, s58, 0x3000
	s_addc_u32 s65, s59, 0
	global_load_dwordx4 v[146:149], v181, s[58:59]
	global_load_dwordx4 v[150:153], v181, s[60:61]
	global_load_dwordx4 v[154:157], v181, s[62:63]
	global_load_dwordx4 v[158:161], v181, s[64:65]
	s_waitcnt vmcnt(4)
	v_cvt_pk_bf16_f32 v190, v130, v134
	v_cvt_pk_bf16_f32 v191, v138, v142
	v_cvt_pk_bf16_f32 v192, v131, v135
	v_cvt_pk_bf16_f32 v193, v139, v143
	ds_write2st64_b64 v180, v[190:191], v[192:193] offset0:0 offset1:4
	v_cvt_pk_bf16_f32 v194, v132, v136
	v_cvt_pk_bf16_f32 v195, v140, v144
	v_cvt_pk_bf16_f32 v190, v133, v137
	v_cvt_pk_bf16_f32 v191, v141, v145
	ds_write2st64_b64 v180, v[194:195], v[190:191] offset0:8 offset1:12
	s_add_i32 s0, s0, 1
	s_and_b32 s58, s0, 31
	s_lshl_b32 s58, s58, 17
	s_add_u32 s58, s4, s58
	s_addc_u32 s59, s5, 0
	s_add_u32 s60, s58, 0x1000
	s_addc_u32 s61, s59, 0
	s_add_u32 s62, s58, s33
	s_addc_u32 s63, s59, 0
	s_add_u32 s64, s58, 0x3000
	s_addc_u32 s65, s59, 0
	global_load_dwordx4 v[130:133], v181, s[58:59]
	global_load_dwordx4 v[134:137], v181, s[60:61]
	global_load_dwordx4 v[138:141], v181, s[62:63]
	global_load_dwordx4 v[142:145], v181, s[64:65]
	ds_read_b128 v[222:225], v174
	ds_read_b128 v[226:229], v174 offset:4096
	s_branch .LBB0_1418
.LBB0_1417:
	s_barrier
	v_lshl_add_u32 v190, s37, 10, v204
	ds_write_b32 v190, v202 offset:61440
	s_waitcnt lgkmcnt(0)
	s_barrier
	v_mov_b32_e32 v196, v199
	s_mul_hi_u32 s0, s41, 0x600
	s_add_u32 s10, s42, s43
	s_addc_u32 s11, s0, 0
	s_lshl_b32 s0, s45, 2
	v_lshl_add_u32 v196, v196, 2, v203
	s_add_i32 s0, s0, 0
	v_lshl_add_u32 v206, v196, 2, s0
	ds_read_b128 v[216:219], v206 offset:61440
	v_mov_b32_e32 v209, v98
	v_mov_b32_e32 v220, v82
	v_mov_b32_e32 v221, v66
	v_or_b32_e32 v82, 1, v196
	v_mov_b32_e32 v98, v115
	v_mov_b32_e32 v66, v83
	s_waitcnt lgkmcnt(0)
	v_pk_mul_f32 v[98:99], v[98:99], v[216:217] op_sel:[0,1]
	v_pk_mul_f32 v[66:67], v[66:67], v[216:217] op_sel:[0,1]
	v_ashrrev_i32_e32 v83, 31, v82
	v_cvt_pk_bf16_f32 v98, v98, v99
	v_cvt_pk_bf16_f32 v99, v66, v67
	v_lshl_add_u64 v[66:67], s[10:11], 0, v[82:83]
	s_and_b32 s0, 0xffff, s40
	v_lshlrev_b64 v[66:67], 11, v[66:67]
	s_lshl_b32 s0, s0, 8
	v_lshl_add_u64 v[66:67], s[90:91], 0, v[66:67]
	v_lshl_add_u64 v[66:67], v[66:67], 0, s[0:1]
	v_lshl_add_u64 v[66:67], v[66:67], 0, v[0:1]
	global_store_dwordx2 v[66:67], v[98:99], off
	v_or_b32_e32 v66, 2, v196
	v_ashrrev_i32_e32 v67, 31, v66
	v_lshl_add_u64 v[66:67], s[10:11], 0, v[66:67]
	v_lshlrev_b64 v[66:67], 11, v[66:67]
	v_mov_b32_e32 v82, v116
	v_mov_b32_e32 v83, v100
	v_mov_b32_e32 v98, v84
	v_mov_b32_e32 v99, v68
	v_lshl_add_u64 v[66:67], s[90:91], 0, v[66:67]
	v_pk_mul_f32 v[82:83], v[82:83], v[218:219] op_sel_hi:[1,0]
	v_pk_mul_f32 v[98:99], v[98:99], v[218:219] op_sel_hi:[1,0]
	v_lshl_add_u64 v[66:67], v[66:67], 0, s[0:1]
	v_cvt_pk_bf16_f32 v82, v82, v83
	v_cvt_pk_bf16_f32 v83, v98, v99
	v_lshl_add_u64 v[66:67], v[66:67], 0, v[0:1]
	v_mov_b32_e32 v208, v114
	global_store_dwordx2 v[66:67], v[82:83], off
	v_or_b32_e32 v66, 3, v196
	v_pk_mul_f32 v[208:209], v[208:209], v[216:217] op_sel_hi:[1,0]
	v_pk_mul_f32 v[220:221], v[220:221], v[216:217] op_sel_hi:[1,0]
	v_ashrrev_i32_e32 v197, 31, v196
	v_ashrrev_i32_e32 v67, 31, v66
	v_cvt_pk_bf16_f32 v208, v208, v209
	v_cvt_pk_bf16_f32 v209, v220, v221
	v_lshl_add_u64 v[220:221], s[10:11], 0, v[196:197]
	v_lshl_add_u64 v[66:67], s[10:11], 0, v[66:67]
	v_lshlrev_b64 v[220:221], 11, v[220:221]
	v_lshlrev_b64 v[66:67], 11, v[66:67]
	v_lshl_add_u64 v[220:221], s[90:91], 0, v[220:221]
	v_mov_b32_e32 v100, v117
	v_mov_b32_e32 v82, v219
	v_mov_b32_e32 v68, v85
	v_lshl_add_u64 v[66:67], s[90:91], 0, v[66:67]
	v_lshl_add_u64 v[220:221], v[220:221], 0, s[0:1]
	v_pk_mul_f32 v[98:99], v[100:101], v[82:83] op_sel_hi:[1,0]
	v_pk_mul_f32 v[68:69], v[68:69], v[82:83] op_sel_hi:[1,0]
	v_lshl_add_u64 v[66:67], v[66:67], 0, s[0:1]
	v_lshl_add_u64 v[220:221], v[220:221], 0, v[0:1]
	v_cvt_pk_bf16_f32 v84, v98, v99
	v_cvt_pk_bf16_f32 v85, v68, v69
	v_lshl_add_u64 v[66:67], v[66:67], 0, v[0:1]
	global_store_dwordx2 v[220:221], v[208:209], off
	global_store_dwordx2 v[66:67], v[84:85], off
	ds_read_b128 v[66:69], v206 offset:61472
	v_add_u32_e32 v82, 8, v196
	v_ashrrev_i32_e32 v83, 31, v82
	v_lshl_add_u64 v[82:83], s[10:11], 0, v[82:83]
	v_lshlrev_b64 v[82:83], 11, v[82:83]
	v_mov_b32_e32 v84, v118
	v_mov_b32_e32 v85, v102
	v_mov_b32_e32 v98, v86
	v_mov_b32_e32 v99, v70
	v_lshl_add_u64 v[82:83], s[90:91], 0, v[82:83]
	s_waitcnt lgkmcnt(0)
	v_pk_mul_f32 v[84:85], v[84:85], v[66:67] op_sel_hi:[1,0]
	v_pk_mul_f32 v[98:99], v[98:99], v[66:67] op_sel_hi:[1,0]
	v_lshl_add_u64 v[82:83], v[82:83], 0, s[0:1]
	v_cvt_pk_bf16_f32 v84, v84, v85
	v_cvt_pk_bf16_f32 v85, v98, v99
	v_lshl_add_u64 v[82:83], v[82:83], 0, v[0:1]
	global_store_dwordx2 v[82:83], v[84:85], off
	v_add_u32_e32 v82, 9, v196
	v_mov_b32_e32 v102, v119
	v_mov_b32_e32 v70, v87
	v_pk_mul_f32 v[84:85], v[102:103], v[66:67] op_sel:[0,1]
	v_pk_mul_f32 v[66:67], v[70:71], v[66:67] op_sel:[0,1]
	v_ashrrev_i32_e32 v83, 31, v82
	v_cvt_pk_bf16_f32 v84, v84, v85
	v_cvt_pk_bf16_f32 v85, v66, v67
	v_lshl_add_u64 v[66:67], s[10:11], 0, v[82:83]
	v_lshlrev_b64 v[66:67], 11, v[66:67]
	v_lshl_add_u64 v[66:67], s[90:91], 0, v[66:67]
	v_lshl_add_u64 v[66:67], v[66:67], 0, s[0:1]
	v_lshl_add_u64 v[66:67], v[66:67], 0, v[0:1]
	global_store_dwordx2 v[66:67], v[84:85], off
	v_add_u32_e32 v66, 10, v196
	v_ashrrev_i32_e32 v67, 31, v66
	v_lshl_add_u64 v[66:67], s[10:11], 0, v[66:67]
	v_lshlrev_b64 v[66:67], 11, v[66:67]
	v_mov_b32_e32 v70, v120
	v_mov_b32_e32 v71, v104
	v_mov_b32_e32 v82, v88
	v_mov_b32_e32 v83, v72
	v_lshl_add_u64 v[66:67], s[90:91], 0, v[66:67]
	v_pk_mul_f32 v[70:71], v[70:71], v[68:69] op_sel_hi:[1,0]
	v_pk_mul_f32 v[82:83], v[82:83], v[68:69] op_sel_hi:[1,0]
	v_lshl_add_u64 v[66:67], v[66:67], 0, s[0:1]
	v_cvt_pk_bf16_f32 v70, v70, v71
	v_cvt_pk_bf16_f32 v71, v82, v83
	v_lshl_add_u64 v[66:67], v[66:67], 0, v[0:1]
	global_store_dwordx2 v[66:67], v[70:71], off
	v_add_u32_e32 v66, 11, v196
	v_ashrrev_i32_e32 v67, 31, v66
	v_lshl_add_u64 v[66:67], s[10:11], 0, v[66:67]
	v_lshlrev_b64 v[66:67], 11, v[66:67]
	v_mov_b32_e32 v104, v121
	v_mov_b32_e32 v68, v69
	v_mov_b32_e32 v72, v89
	v_lshl_add_u64 v[66:67], s[90:91], 0, v[66:67]
	v_pk_mul_f32 v[70:71], v[104:105], v[68:69] op_sel_hi:[1,0]
	v_pk_mul_f32 v[68:69], v[72:73], v[68:69] op_sel_hi:[1,0]
	v_lshl_add_u64 v[66:67], v[66:67], 0, s[0:1]
	v_cvt_pk_bf16_f32 v70, v70, v71
	v_cvt_pk_bf16_f32 v71, v68, v69
	v_lshl_add_u64 v[66:67], v[66:67], 0, v[0:1]
	global_store_dwordx2 v[66:67], v[70:71], off
	ds_read_b128 v[66:69], v206 offset:61504
	v_add_u32_e32 v70, 16, v196
	v_ashrrev_i32_e32 v71, 31, v70
	v_lshl_add_u64 v[70:71], s[10:11], 0, v[70:71]
	v_lshlrev_b64 v[70:71], 11, v[70:71]
	v_mov_b32_e32 v72, v122
	v_mov_b32_e32 v73, v106
	v_mov_b32_e32 v82, v90
	v_mov_b32_e32 v83, v74
	v_lshl_add_u64 v[70:71], s[90:91], 0, v[70:71]
	s_waitcnt lgkmcnt(0)
	v_pk_mul_f32 v[72:73], v[72:73], v[66:67] op_sel_hi:[1,0]
	v_pk_mul_f32 v[82:83], v[82:83], v[66:67] op_sel_hi:[1,0]
	v_lshl_add_u64 v[70:71], v[70:71], 0, s[0:1]
	v_cvt_pk_bf16_f32 v72, v72, v73
	v_cvt_pk_bf16_f32 v73, v82, v83
	v_lshl_add_u64 v[70:71], v[70:71], 0, v[0:1]
	global_store_dwordx2 v[70:71], v[72:73], off
	v_add_u32_e32 v70, 17, v196
	v_mov_b32_e32 v106, v123
	v_mov_b32_e32 v74, v91
	v_pk_mul_f32 v[72:73], v[106:107], v[66:67] op_sel:[0,1]
	v_pk_mul_f32 v[66:67], v[74:75], v[66:67] op_sel:[0,1]
	v_ashrrev_i32_e32 v71, 31, v70
	v_cvt_pk_bf16_f32 v72, v72, v73
	v_cvt_pk_bf16_f32 v73, v66, v67
	v_lshl_add_u64 v[66:67], s[10:11], 0, v[70:71]
	v_lshlrev_b64 v[66:67], 11, v[66:67]
	v_lshl_add_u64 v[66:67], s[90:91], 0, v[66:67]
	v_lshl_add_u64 v[66:67], v[66:67], 0, s[0:1]
	v_lshl_add_u64 v[66:67], v[66:67], 0, v[0:1]
	global_store_dwordx2 v[66:67], v[72:73], off
	v_add_u32_e32 v66, 18, v196
	v_ashrrev_i32_e32 v67, 31, v66
	v_lshl_add_u64 v[66:67], s[10:11], 0, v[66:67]
	v_lshlrev_b64 v[66:67], 11, v[66:67]
	v_mov_b32_e32 v70, v124
	v_mov_b32_e32 v71, v108
	v_mov_b32_e32 v72, v92
	v_mov_b32_e32 v73, v76
	v_lshl_add_u64 v[66:67], s[90:91], 0, v[66:67]
	v_pk_mul_f32 v[70:71], v[70:71], v[68:69] op_sel_hi:[1,0]
	v_pk_mul_f32 v[72:73], v[72:73], v[68:69] op_sel_hi:[1,0]
	v_lshl_add_u64 v[66:67], v[66:67], 0, s[0:1]
	v_cvt_pk_bf16_f32 v70, v70, v71
	v_cvt_pk_bf16_f32 v71, v72, v73
	v_lshl_add_u64 v[66:67], v[66:67], 0, v[0:1]
	global_store_dwordx2 v[66:67], v[70:71], off
	v_add_u32_e32 v66, 19, v196
	v_ashrrev_i32_e32 v67, 31, v66
	v_lshl_add_u64 v[66:67], s[10:11], 0, v[66:67]
	v_lshlrev_b64 v[66:67], 11, v[66:67]
	v_mov_b32_e32 v108, v125
	v_mov_b32_e32 v68, v69
	v_mov_b32_e32 v76, v93
	v_lshl_add_u64 v[66:67], s[90:91], 0, v[66:67]
	v_pk_mul_f32 v[70:71], v[108:109], v[68:69] op_sel_hi:[1,0]
	v_pk_mul_f32 v[68:69], v[76:77], v[68:69] op_sel_hi:[1,0]
	v_lshl_add_u64 v[66:67], v[66:67], 0, s[0:1]
	v_cvt_pk_bf16_f32 v70, v70, v71
	v_cvt_pk_bf16_f32 v71, v68, v69
	v_lshl_add_u64 v[66:67], v[66:67], 0, v[0:1]
	global_store_dwordx2 v[66:67], v[70:71], off
	ds_read_b128 v[66:69], v206 offset:61536
	v_add_u32_e32 v70, 24, v196
	v_ashrrev_i32_e32 v71, 31, v70
	v_lshl_add_u64 v[70:71], s[10:11], 0, v[70:71]
	v_lshlrev_b64 v[70:71], 11, v[70:71]
	v_mov_b32_e32 v72, v126
	v_mov_b32_e32 v73, v110
	v_mov_b32_e32 v74, v94
	v_mov_b32_e32 v75, v78
	v_lshl_add_u64 v[70:71], s[90:91], 0, v[70:71]
	s_waitcnt lgkmcnt(0)
	v_pk_mul_f32 v[72:73], v[72:73], v[66:67] op_sel_hi:[1,0]
	v_pk_mul_f32 v[74:75], v[74:75], v[66:67] op_sel_hi:[1,0]
	v_lshl_add_u64 v[70:71], v[70:71], 0, s[0:1]
	v_cvt_pk_bf16_f32 v72, v72, v73
	v_cvt_pk_bf16_f32 v73, v74, v75
	v_lshl_add_u64 v[70:71], v[70:71], 0, v[0:1]
	global_store_dwordx2 v[70:71], v[72:73], off
	v_add_u32_e32 v70, 25, v196
	v_mov_b32_e32 v110, v127
	v_mov_b32_e32 v78, v95
	v_pk_mul_f32 v[72:73], v[110:111], v[66:67] op_sel:[0,1]
	v_pk_mul_f32 v[66:67], v[78:79], v[66:67] op_sel:[0,1]
	v_ashrrev_i32_e32 v71, 31, v70
	v_cvt_pk_bf16_f32 v72, v72, v73
	v_cvt_pk_bf16_f32 v73, v66, v67
	v_lshl_add_u64 v[66:67], s[10:11], 0, v[70:71]
	v_lshlrev_b64 v[66:67], 11, v[66:67]
	v_lshl_add_u64 v[66:67], s[90:91], 0, v[66:67]
	v_lshl_add_u64 v[66:67], v[66:67], 0, s[0:1]
	v_lshl_add_u64 v[66:67], v[66:67], 0, v[0:1]
	global_store_dwordx2 v[66:67], v[72:73], off
	v_add_u32_e32 v66, 26, v196
	v_ashrrev_i32_e32 v67, 31, v66
	v_lshl_add_u64 v[66:67], s[10:11], 0, v[66:67]
	v_lshlrev_b64 v[66:67], 11, v[66:67]
	v_mov_b32_e32 v70, v128
	v_mov_b32_e32 v71, v112
	v_mov_b32_e32 v72, v96
	v_mov_b32_e32 v73, v80
	v_lshl_add_u64 v[66:67], s[90:91], 0, v[66:67]
	v_pk_mul_f32 v[70:71], v[70:71], v[68:69] op_sel_hi:[1,0]
	v_pk_mul_f32 v[72:73], v[72:73], v[68:69] op_sel_hi:[1,0]
	v_lshl_add_u64 v[66:67], v[66:67], 0, s[0:1]
	v_cvt_pk_bf16_f32 v70, v70, v71
	v_cvt_pk_bf16_f32 v71, v72, v73
	v_lshl_add_u64 v[66:67], v[66:67], 0, v[0:1]
	global_store_dwordx2 v[66:67], v[70:71], off
	v_add_u32_e32 v66, 27, v196
	v_ashrrev_i32_e32 v67, 31, v66
	v_lshl_add_u64 v[66:67], s[10:11], 0, v[66:67]
	v_lshlrev_b64 v[66:67], 11, v[66:67]
	v_mov_b32_e32 v112, v129
	v_mov_b32_e32 v68, v69
	v_mov_b32_e32 v80, v97
	v_lshl_add_u64 v[66:67], s[90:91], 0, v[66:67]
	v_pk_mul_f32 v[70:71], v[112:113], v[68:69] op_sel_hi:[1,0]
	v_pk_mul_f32 v[68:69], v[80:81], v[68:69] op_sel_hi:[1,0]
	v_lshl_add_u64 v[66:67], v[66:67], 0, s[0:1]
	v_cvt_pk_bf16_f32 v70, v70, v71
	v_cvt_pk_bf16_f32 v71, v68, v69
	v_lshl_add_u64 v[66:67], v[66:67], 0, v[0:1]
	global_store_dwordx2 v[66:67], v[70:71], off
	ds_read_b128 v[66:69], v206 offset:61568
	v_mov_b32_e32 v73, v34
	v_mov_b32_e32 v74, v18
	v_mov_b32_e32 v75, v2
	v_add_u32_e32 v18, 33, v196
	v_mov_b32_e32 v34, v51
	v_mov_b32_e32 v2, v19
	s_waitcnt lgkmcnt(0)
	v_pk_mul_f32 v[34:35], v[34:35], v[66:67] op_sel:[0,1]
	v_pk_mul_f32 v[2:3], v[2:3], v[66:67] op_sel:[0,1]
	v_ashrrev_i32_e32 v19, 31, v18
	v_cvt_pk_bf16_f32 v34, v34, v35
	v_cvt_pk_bf16_f32 v35, v2, v3
	v_lshl_add_u64 v[2:3], s[10:11], 0, v[18:19]
	v_lshlrev_b64 v[2:3], 11, v[2:3]
	v_lshl_add_u64 v[2:3], s[90:91], 0, v[2:3]
	v_lshl_add_u64 v[2:3], v[2:3], 0, s[0:1]
	v_lshl_add_u64 v[2:3], v[2:3], 0, v[0:1]
	global_store_dwordx2 v[2:3], v[34:35], off
	v_add_u32_e32 v2, 34, v196
	v_ashrrev_i32_e32 v3, 31, v2
	v_lshl_add_u64 v[2:3], s[10:11], 0, v[2:3]
	v_lshlrev_b64 v[2:3], 11, v[2:3]
	v_mov_b32_e32 v18, v52
	v_mov_b32_e32 v19, v36
	v_mov_b32_e32 v34, v20
	v_mov_b32_e32 v35, v4
	v_lshl_add_u64 v[2:3], s[90:91], 0, v[2:3]
	v_pk_mul_f32 v[18:19], v[18:19], v[68:69] op_sel_hi:[1,0]
	v_pk_mul_f32 v[34:35], v[34:35], v[68:69] op_sel_hi:[1,0]
	v_lshl_add_u64 v[2:3], v[2:3], 0, s[0:1]
	v_cvt_pk_bf16_f32 v18, v18, v19
	v_cvt_pk_bf16_f32 v19, v34, v35
	v_lshl_add_u64 v[2:3], v[2:3], 0, v[0:1]
	v_add_u32_e32 v70, 32, v196
	global_store_dwordx2 v[2:3], v[18:19], off
	v_add_u32_e32 v2, 35, v196
	v_ashrrev_i32_e32 v71, 31, v70
	v_ashrrev_i32_e32 v3, 31, v2
	v_lshl_add_u64 v[70:71], s[10:11], 0, v[70:71]
	v_lshl_add_u64 v[2:3], s[10:11], 0, v[2:3]
	v_lshlrev_b64 v[70:71], 11, v[70:71]
	v_lshlrev_b64 v[2:3], 11, v[2:3]
	v_mov_b32_e32 v72, v50
	v_lshl_add_u64 v[70:71], s[90:91], 0, v[70:71]
	v_mov_b32_e32 v36, v53
	v_mov_b32_e32 v18, v69
	v_mov_b32_e32 v4, v21
	v_lshl_add_u64 v[2:3], s[90:91], 0, v[2:3]
	v_pk_mul_f32 v[72:73], v[72:73], v[66:67] op_sel_hi:[1,0]
	v_pk_mul_f32 v[74:75], v[74:75], v[66:67] op_sel_hi:[1,0]
	v_lshl_add_u64 v[70:71], v[70:71], 0, s[0:1]
	v_pk_mul_f32 v[34:35], v[36:37], v[18:19] op_sel_hi:[1,0]
	v_pk_mul_f32 v[4:5], v[4:5], v[18:19] op_sel_hi:[1,0]
	v_lshl_add_u64 v[2:3], v[2:3], 0, s[0:1]
	v_cvt_pk_bf16_f32 v72, v72, v73
	v_cvt_pk_bf16_f32 v73, v74, v75
	v_lshl_add_u64 v[70:71], v[70:71], 0, v[0:1]
	v_cvt_pk_bf16_f32 v20, v34, v35
	v_cvt_pk_bf16_f32 v21, v4, v5
	v_lshl_add_u64 v[2:3], v[2:3], 0, v[0:1]
	global_store_dwordx2 v[70:71], v[72:73], off
	global_store_dwordx2 v[2:3], v[20:21], off
	ds_read_b128 v[2:5], v206 offset:61600
	v_add_u32_e32 v18, 40, v196
	v_ashrrev_i32_e32 v19, 31, v18
	v_lshl_add_u64 v[18:19], s[10:11], 0, v[18:19]
	v_lshlrev_b64 v[18:19], 11, v[18:19]
	v_mov_b32_e32 v20, v54
	v_mov_b32_e32 v21, v38
	v_mov_b32_e32 v34, v22
	v_mov_b32_e32 v35, v6
	v_lshl_add_u64 v[18:19], s[90:91], 0, v[18:19]
	s_waitcnt lgkmcnt(0)
	v_pk_mul_f32 v[20:21], v[20:21], v[2:3] op_sel_hi:[1,0]
	v_pk_mul_f32 v[34:35], v[34:35], v[2:3] op_sel_hi:[1,0]
	v_lshl_add_u64 v[18:19], v[18:19], 0, s[0:1]
	v_cvt_pk_bf16_f32 v20, v20, v21
	v_cvt_pk_bf16_f32 v21, v34, v35
	v_lshl_add_u64 v[18:19], v[18:19], 0, v[0:1]
	global_store_dwordx2 v[18:19], v[20:21], off
	v_add_u32_e32 v18, 41, v196
	v_mov_b32_e32 v38, v55
	v_mov_b32_e32 v6, v23
	v_pk_mul_f32 v[20:21], v[38:39], v[2:3] op_sel:[0,1]
	v_pk_mul_f32 v[2:3], v[6:7], v[2:3] op_sel:[0,1]
	v_ashrrev_i32_e32 v19, 31, v18
	v_cvt_pk_bf16_f32 v20, v20, v21
	v_cvt_pk_bf16_f32 v21, v2, v3
	v_lshl_add_u64 v[2:3], s[10:11], 0, v[18:19]
	v_lshlrev_b64 v[2:3], 11, v[2:3]
	v_lshl_add_u64 v[2:3], s[90:91], 0, v[2:3]
	v_lshl_add_u64 v[2:3], v[2:3], 0, s[0:1]
	v_lshl_add_u64 v[2:3], v[2:3], 0, v[0:1]
	global_store_dwordx2 v[2:3], v[20:21], off
	v_add_u32_e32 v2, 42, v196
	v_ashrrev_i32_e32 v3, 31, v2
	v_lshl_add_u64 v[2:3], s[10:11], 0, v[2:3]
	v_lshlrev_b64 v[2:3], 11, v[2:3]
	v_mov_b32_e32 v6, v56
	v_mov_b32_e32 v7, v40
	v_mov_b32_e32 v18, v24
	v_mov_b32_e32 v19, v8
	v_lshl_add_u64 v[2:3], s[90:91], 0, v[2:3]
	v_pk_mul_f32 v[6:7], v[6:7], v[4:5] op_sel_hi:[1,0]
	v_pk_mul_f32 v[18:19], v[18:19], v[4:5] op_sel_hi:[1,0]
	v_lshl_add_u64 v[2:3], v[2:3], 0, s[0:1]
	v_cvt_pk_bf16_f32 v6, v6, v7
	v_cvt_pk_bf16_f32 v7, v18, v19
	v_lshl_add_u64 v[2:3], v[2:3], 0, v[0:1]
	global_store_dwordx2 v[2:3], v[6:7], off
	v_add_u32_e32 v2, 43, v196
	v_ashrrev_i32_e32 v3, 31, v2
	v_lshl_add_u64 v[2:3], s[10:11], 0, v[2:3]
	v_lshlrev_b64 v[2:3], 11, v[2:3]
	v_mov_b32_e32 v40, v57
	v_mov_b32_e32 v4, v5
	v_mov_b32_e32 v8, v25
	v_lshl_add_u64 v[2:3], s[90:91], 0, v[2:3]
	v_pk_mul_f32 v[6:7], v[40:41], v[4:5] op_sel_hi:[1,0]
	v_pk_mul_f32 v[4:5], v[8:9], v[4:5] op_sel_hi:[1,0]
	v_lshl_add_u64 v[2:3], v[2:3], 0, s[0:1]
	v_cvt_pk_bf16_f32 v6, v6, v7
	v_cvt_pk_bf16_f32 v7, v4, v5
	v_lshl_add_u64 v[2:3], v[2:3], 0, v[0:1]
	global_store_dwordx2 v[2:3], v[6:7], off
	ds_read_b128 v[2:5], v206 offset:61632
	v_add_u32_e32 v6, 48, v196
	v_ashrrev_i32_e32 v7, 31, v6
	v_lshl_add_u64 v[6:7], s[10:11], 0, v[6:7]
	v_lshlrev_b64 v[6:7], 11, v[6:7]
	v_mov_b32_e32 v8, v58
	v_mov_b32_e32 v9, v42
	v_mov_b32_e32 v18, v26
	v_mov_b32_e32 v19, v10
	v_lshl_add_u64 v[6:7], s[90:91], 0, v[6:7]
	s_waitcnt lgkmcnt(0)
	v_pk_mul_f32 v[8:9], v[8:9], v[2:3] op_sel_hi:[1,0]
	v_pk_mul_f32 v[18:19], v[18:19], v[2:3] op_sel_hi:[1,0]
	v_lshl_add_u64 v[6:7], v[6:7], 0, s[0:1]
	v_cvt_pk_bf16_f32 v8, v8, v9
	v_cvt_pk_bf16_f32 v9, v18, v19
	v_lshl_add_u64 v[6:7], v[6:7], 0, v[0:1]
	global_store_dwordx2 v[6:7], v[8:9], off
	v_add_u32_e32 v6, 49, v196
	v_mov_b32_e32 v42, v59
	v_mov_b32_e32 v10, v27
	v_pk_mul_f32 v[8:9], v[42:43], v[2:3] op_sel:[0,1]
	v_pk_mul_f32 v[2:3], v[10:11], v[2:3] op_sel:[0,1]
	v_ashrrev_i32_e32 v7, 31, v6
	v_cvt_pk_bf16_f32 v8, v8, v9
	v_cvt_pk_bf16_f32 v9, v2, v3
	v_lshl_add_u64 v[2:3], s[10:11], 0, v[6:7]
	v_lshlrev_b64 v[2:3], 11, v[2:3]
	v_lshl_add_u64 v[2:3], s[90:91], 0, v[2:3]
	v_lshl_add_u64 v[2:3], v[2:3], 0, s[0:1]
	v_lshl_add_u64 v[2:3], v[2:3], 0, v[0:1]
	global_store_dwordx2 v[2:3], v[8:9], off
	v_add_u32_e32 v2, 50, v196
	v_ashrrev_i32_e32 v3, 31, v2
	v_lshl_add_u64 v[2:3], s[10:11], 0, v[2:3]
	v_lshlrev_b64 v[2:3], 11, v[2:3]
	v_mov_b32_e32 v6, v60
	v_mov_b32_e32 v7, v44
	v_mov_b32_e32 v8, v28
	v_mov_b32_e32 v9, v12
	v_lshl_add_u64 v[2:3], s[90:91], 0, v[2:3]
	v_pk_mul_f32 v[6:7], v[6:7], v[4:5] op_sel_hi:[1,0]
	v_pk_mul_f32 v[8:9], v[8:9], v[4:5] op_sel_hi:[1,0]
	v_lshl_add_u64 v[2:3], v[2:3], 0, s[0:1]
	v_cvt_pk_bf16_f32 v6, v6, v7
	v_cvt_pk_bf16_f32 v7, v8, v9
	v_lshl_add_u64 v[2:3], v[2:3], 0, v[0:1]
	global_store_dwordx2 v[2:3], v[6:7], off
	v_add_u32_e32 v2, 51, v196
	v_ashrrev_i32_e32 v3, 31, v2
	v_lshl_add_u64 v[2:3], s[10:11], 0, v[2:3]
	v_lshlrev_b64 v[2:3], 11, v[2:3]
	v_mov_b32_e32 v44, v61
	v_mov_b32_e32 v4, v5
	v_mov_b32_e32 v12, v29
	v_lshl_add_u64 v[2:3], s[90:91], 0, v[2:3]
	v_pk_mul_f32 v[6:7], v[44:45], v[4:5] op_sel_hi:[1,0]
	v_pk_mul_f32 v[4:5], v[12:13], v[4:5] op_sel_hi:[1,0]
	v_lshl_add_u64 v[2:3], v[2:3], 0, s[0:1]
	v_cvt_pk_bf16_f32 v6, v6, v7
	v_cvt_pk_bf16_f32 v7, v4, v5
	v_lshl_add_u64 v[2:3], v[2:3], 0, v[0:1]
	global_store_dwordx2 v[2:3], v[6:7], off
	ds_read_b128 v[2:5], v206 offset:61664
	v_add_u32_e32 v6, 56, v196
	v_ashrrev_i32_e32 v7, 31, v6
	v_lshl_add_u64 v[6:7], s[10:11], 0, v[6:7]
	v_lshlrev_b64 v[6:7], 11, v[6:7]
	v_mov_b32_e32 v8, v62
	v_mov_b32_e32 v9, v46
	v_mov_b32_e32 v10, v30
	v_mov_b32_e32 v11, v14
	v_lshl_add_u64 v[6:7], s[90:91], 0, v[6:7]
	s_waitcnt lgkmcnt(0)
	v_pk_mul_f32 v[8:9], v[8:9], v[2:3] op_sel_hi:[1,0]
	v_pk_mul_f32 v[10:11], v[10:11], v[2:3] op_sel_hi:[1,0]
	v_lshl_add_u64 v[6:7], v[6:7], 0, s[0:1]
	v_cvt_pk_bf16_f32 v8, v8, v9
	v_cvt_pk_bf16_f32 v9, v10, v11
	v_lshl_add_u64 v[6:7], v[6:7], 0, v[0:1]
	global_store_dwordx2 v[6:7], v[8:9], off
	v_add_u32_e32 v6, 57, v196
	v_mov_b32_e32 v46, v63
	v_mov_b32_e32 v14, v31
	v_pk_mul_f32 v[8:9], v[46:47], v[2:3] op_sel:[0,1]
	v_pk_mul_f32 v[2:3], v[14:15], v[2:3] op_sel:[0,1]
	v_ashrrev_i32_e32 v7, 31, v6
	v_cvt_pk_bf16_f32 v8, v8, v9
	v_cvt_pk_bf16_f32 v9, v2, v3
	v_lshl_add_u64 v[2:3], s[10:11], 0, v[6:7]
	v_lshlrev_b64 v[2:3], 11, v[2:3]
	v_lshl_add_u64 v[2:3], s[90:91], 0, v[2:3]
	v_lshl_add_u64 v[2:3], v[2:3], 0, s[0:1]
	v_lshl_add_u64 v[2:3], v[2:3], 0, v[0:1]
	global_store_dwordx2 v[2:3], v[8:9], off
	v_add_u32_e32 v2, 58, v196
	v_ashrrev_i32_e32 v3, 31, v2
	v_lshl_add_u64 v[2:3], s[10:11], 0, v[2:3]
	v_lshlrev_b64 v[2:3], 11, v[2:3]
	v_mov_b32_e32 v6, v64
	v_mov_b32_e32 v7, v48
	v_mov_b32_e32 v8, v32
	v_mov_b32_e32 v9, v16
	v_lshl_add_u64 v[2:3], s[90:91], 0, v[2:3]
	v_pk_mul_f32 v[6:7], v[6:7], v[4:5] op_sel_hi:[1,0]
	v_pk_mul_f32 v[8:9], v[8:9], v[4:5] op_sel_hi:[1,0]
	v_lshl_add_u64 v[2:3], v[2:3], 0, s[0:1]
	v_cvt_pk_bf16_f32 v6, v6, v7
	v_cvt_pk_bf16_f32 v7, v8, v9
	v_lshl_add_u64 v[2:3], v[2:3], 0, v[0:1]
	global_store_dwordx2 v[2:3], v[6:7], off
	v_add_u32_e32 v2, 59, v196
	v_ashrrev_i32_e32 v3, 31, v2
	v_lshl_add_u64 v[2:3], s[10:11], 0, v[2:3]
	v_lshlrev_b64 v[2:3], 11, v[2:3]
	v_mov_b32_e32 v48, v65
	v_mov_b32_e32 v4, v5
	v_mov_b32_e32 v16, v33
	v_lshl_add_u64 v[2:3], s[90:91], 0, v[2:3]
	v_pk_mul_f32 v[6:7], v[48:49], v[4:5] op_sel_hi:[1,0]
	v_pk_mul_f32 v[4:5], v[16:17], v[4:5] op_sel_hi:[1,0]
	v_lshl_add_u64 v[2:3], v[2:3], 0, s[0:1]
	v_cvt_pk_bf16_f32 v6, v6, v7
	v_cvt_pk_bf16_f32 v7, v4, v5
	v_lshl_add_u64 v[2:3], v[2:3], 0, v[0:1]
	global_store_dwordx2 v[2:3], v[6:7], off
	s_and_b64 vcc, exec, s[8:9]
	s_cbranch_vccnz .LBB0_1425
.LBB0_1418:
	s_mul_hi_u32 s0, s38, 0xaaaaaaab
	s_lshr_b32 s0, s0, 5
	v_readlane_b32 s8, v245, 12
	s_add_i32 s41, s0, s8
	s_mul_i32 s0, s0, 48
	s_sub_i32 s0, s38, s0
	s_mul_i32 s8, s0, 0xab
	s_bfe_u32 s40, s8, 0x6000a
	s_mul_i32 s8, s40, 6
	s_sub_i32 s0, s0, s8
	s_and_b32 s0, s0, 0xff
	s_mul_i32 s42, s41, 0x600
	s_lshl_b32 s43, s0, 8
	s_add_i32 s0, s43, s42
	v_add_u32_e32 v2, s0, v198
	v_readlane_b32 s44, v247, 49
	v_ashrrev_i32_e32 v3, 31, v2
	v_readlane_b32 s58, v247, 63
	v_readlane_b32 s59, v246, 0
	s_xor_b32 s37, s37, 1
	s_add_i32 s38, s38, s86
	v_lshl_add_u64 v[2:3], v[2:3], 2, s[58:59]
	global_load_dword v202, v[2:3], off
	s_cmp_ge_i32 s38, s34
	s_cselect_b64 s[8:9], -1, 0
	v_lshl_add_u32 v3, s37, 10, v204
	s_and_b64 vcc, exec, s[8:9]
	s_mov_b64 s[10:11], s[6:7]
	s_mov_b64 s[12:13], s[4:5]
	s_mov_b32 s44, s39
	v_readlane_b32 s45, v247, 50
	v_readlane_b32 s46, v247, 51
	v_readlane_b32 s47, v247, 52
	v_readlane_b32 s48, v247, 53
	v_readlane_b32 s49, v247, 54
	v_readlane_b32 s50, v247, 55
	v_readlane_b32 s51, v247, 56
	v_readlane_b32 s52, v247, 57
	v_readlane_b32 s53, v247, 58
	v_readlane_b32 s54, v247, 59
	v_readlane_b32 s55, v247, 60
	v_readlane_b32 s56, v247, 61
	v_readlane_b32 s57, v247, 62
	s_waitcnt vmcnt(0)
	s_nop 0
	s_cbranch_vccnz .LBB0_1420
	s_mul_hi_u32 s44, s38, 0xaaaaaaab
	s_lshr_b32 s10, s44, 5
	v_readlane_b32 s0, v245, 12
	s_add_i32 s0, s10, s0
	s_mul_i32 s10, s10, 48
	s_sub_i32 s10, s38, s10
	s_mul_i32 s11, s10, 0xab
	s_bfe_u32 s45, s11, 0x6000a
	s_mul_i32 s11, s45, 6
	s_sub_i32 s10, s10, s11
	s_and_b32 s10, s10, 0xff
	s_lshl_b32 s10, s10, 19
	s_add_u32 s10, s24, s10
	s_mul_i32 s12, s0, 0x300000
	s_addc_u32 s13, s25, 0
	s_mul_hi_u32 s11, s0, 0x300000
	s_add_u32 s10, s10, s12
	s_addc_u32 s11, s13, s11
	s_lshl_b64 s[12:13], s[0:1], 22
	s_add_u32 s0, s35, s12
	s_addc_u32 s13, s36, s13
	s_lshl_b32 s12, s45, 9
	s_add_u32 s12, s0, s12
	s_addc_u32 s13, s13, 0
	s_lshr_b32 s0, s44, 2
	s_mul_i32 s0, s0, 6
	s_sub_i32 s0, s38, s0
	s_bfe_u32 s44, s44, 0x10002
	s_add_i32 s44, s44, s0
.LBB0_1420:
	v_mov_b32_e32 v2, 0
	s_lshl_b32 s45, s37, 8
	s_mov_b32 s46, 0
	s_mov_b32 s74, 2
	v_mov_b32_e32 v3, v2
	v_mov_b32_e32 v4, v2
	v_mov_b32_e32 v5, v2
	v_mov_b32_e32 v6, v2
	v_mov_b32_e32 v7, v2
	v_mov_b32_e32 v8, v2
	v_mov_b32_e32 v9, v2
	v_mov_b32_e32 v10, v2
	v_mov_b32_e32 v11, v2
	v_mov_b32_e32 v12, v2
	v_mov_b32_e32 v13, v2
	v_mov_b32_e32 v14, v2
	v_mov_b32_e32 v15, v2
	v_mov_b32_e32 v16, v2
	v_mov_b32_e32 v17, v2
	v_mov_b32_e32 v18, v2
	v_mov_b32_e32 v19, v2
	v_mov_b32_e32 v20, v2
	v_mov_b32_e32 v21, v2
	v_mov_b32_e32 v22, v2
	v_mov_b32_e32 v23, v2
	v_mov_b32_e32 v24, v2
	v_mov_b32_e32 v25, v2
	v_mov_b32_e32 v26, v2
	v_mov_b32_e32 v27, v2
	v_mov_b32_e32 v28, v2
	v_mov_b32_e32 v29, v2
	v_mov_b32_e32 v30, v2
	v_mov_b32_e32 v31, v2
	v_mov_b32_e32 v32, v2
	v_mov_b32_e32 v33, v2
	v_mov_b32_e32 v34, v2
	v_mov_b32_e32 v35, v2
	v_mov_b32_e32 v36, v2
	v_mov_b32_e32 v37, v2
	v_mov_b32_e32 v38, v2
	v_mov_b32_e32 v39, v2
	v_mov_b32_e32 v40, v2
	v_mov_b32_e32 v41, v2
	v_mov_b32_e32 v42, v2
	v_mov_b32_e32 v43, v2
	v_mov_b32_e32 v44, v2
	v_mov_b32_e32 v45, v2
	v_mov_b32_e32 v46, v2
	v_mov_b32_e32 v47, v2
	v_mov_b32_e32 v48, v2
	v_mov_b32_e32 v49, v2
	v_mov_b32_e32 v50, v2
	v_mov_b32_e32 v51, v2
	v_mov_b32_e32 v52, v2
	v_mov_b32_e32 v53, v2
	v_mov_b32_e32 v54, v2
	v_mov_b32_e32 v55, v2
	v_mov_b32_e32 v56, v2
	v_mov_b32_e32 v57, v2
	v_mov_b32_e32 v58, v2
	v_mov_b32_e32 v59, v2
	v_mov_b32_e32 v60, v2
	v_mov_b32_e32 v61, v2
	v_mov_b32_e32 v62, v2
	v_mov_b32_e32 v63, v2
	v_mov_b32_e32 v64, v2
	v_mov_b32_e32 v65, v2
	v_mov_b32_e32 v66, v2
	v_mov_b32_e32 v67, v2
	v_mov_b32_e32 v68, v2
	v_mov_b32_e32 v69, v2
	v_mov_b32_e32 v70, v2
	v_mov_b32_e32 v71, v2
	v_mov_b32_e32 v72, v2
	v_mov_b32_e32 v73, v2
	v_mov_b32_e32 v74, v2
	v_mov_b32_e32 v75, v2
	v_mov_b32_e32 v76, v2
	v_mov_b32_e32 v77, v2
	v_mov_b32_e32 v78, v2
	v_mov_b32_e32 v79, v2
	v_mov_b32_e32 v80, v2
	v_mov_b32_e32 v81, v2
	v_mov_b32_e32 v82, v2
	v_mov_b32_e32 v83, v2
	v_mov_b32_e32 v84, v2
	v_mov_b32_e32 v85, v2
	v_mov_b32_e32 v86, v2
	v_mov_b32_e32 v87, v2
	v_mov_b32_e32 v88, v2
	v_mov_b32_e32 v89, v2
	v_mov_b32_e32 v90, v2
	v_mov_b32_e32 v91, v2
	v_mov_b32_e32 v92, v2
	v_mov_b32_e32 v93, v2
	v_mov_b32_e32 v94, v2
	v_mov_b32_e32 v95, v2
	v_mov_b32_e32 v96, v2
	v_mov_b32_e32 v97, v2
	v_mov_b32_e32 v98, v2
	v_mov_b32_e32 v99, v2
	v_mov_b32_e32 v100, v2
	v_mov_b32_e32 v101, v2
	v_mov_b32_e32 v102, v2
	v_mov_b32_e32 v103, v2
	v_mov_b32_e32 v104, v2
	v_mov_b32_e32 v105, v2
	v_mov_b32_e32 v106, v2
	v_mov_b32_e32 v107, v2
	v_mov_b32_e32 v108, v2
	v_mov_b32_e32 v109, v2
	v_mov_b32_e32 v110, v2
	v_mov_b32_e32 v111, v2
	v_mov_b32_e32 v112, v2
	v_mov_b32_e32 v113, v2
	v_mov_b32_e32 v114, v2
	v_mov_b32_e32 v115, v2
	v_mov_b32_e32 v116, v2
	v_mov_b32_e32 v117, v2
	v_mov_b32_e32 v118, v2
	v_mov_b32_e32 v119, v2
	v_mov_b32_e32 v120, v2
	v_mov_b32_e32 v121, v2
	v_mov_b32_e32 v122, v2
	v_mov_b32_e32 v123, v2
	v_mov_b32_e32 v124, v2
	v_mov_b32_e32 v125, v2
	v_mov_b32_e32 v126, v2
	v_mov_b32_e32 v127, v2
	v_mov_b32_e32 v128, v2
	v_mov_b32_e32 v129, v2
	s_branch .Lg7_loop
.Lg7_switch:
	s_mov_b64 s[4:5], s[12:13]
	s_mov_b64 s[6:7], s[10:11]
	s_add_u32 s70, s6, 0xfffff000
	s_addc_u32 s71, s7, -1
	s_mov_b32 s39, s44
	s_mov_b32 s74, -2
	s_branch .Lg7_noswitch
.Lg7_loop:
	s_waitcnt lgkmcnt(0)
	s_barrier
	ds_read_b128 v[230:233], v178
	ds_read_b128 v[234:237], v178 offset:2048
	ds_read_b128 v[238:241], v178 offset:4096
	ds_read_b128 v[248:251], v178 offset:6144
	ds_read_b128 v[252:255], v175
	ds_read_b128 v[170:173], v175 offset:4096
	s_lshl_b32 s0, s39, 1
	s_add_i32 s0, s0, s74
	s_and_b32 s66, s0, 30
	s_lshl_b32 s66, s66, 6
	s_add_u32 s66, s70, s66
	s_addc_u32 s67, s71, 0
	s_add_i32 s32, s75, s76
	s_mov_b32 m0, s32
	s_waitcnt lgkmcnt(5)
	v_mfma_f32_32x32x16_bf16 v[114:129], v[222:225], v[230:233], v[114:129]
	global_load_lds_dwordx4 v162, s[66:67]
	v_mfma_f32_32x32x16_bf16 v[50:65], v[226:229], v[230:233], v[50:65]
	ds_read_b128 v[230:233], v179
	s_waitcnt lgkmcnt(5)
	v_mfma_f32_32x32x16_bf16 v[98:113], v[222:225], v[234:237], v[98:113]
	global_load_lds_dwordx4 v163, s[66:67] offset:1024
	v_mfma_f32_32x32x16_bf16 v[34:49], v[226:229], v[234:237], v[34:49]
	ds_read_b128 v[234:237], v179 offset:2048
	s_waitcnt lgkmcnt(5)
	v_mfma_f32_32x32x16_bf16 v[82:97], v[222:225], v[238:241], v[82:97]
	global_load_lds_dwordx4 v164, s[66:67] offset:2048
	v_mfma_f32_32x32x16_bf16 v[18:33], v[226:229], v[238:241], v[18:33]
	ds_read_b128 v[238:241], v179 offset:4096
	s_waitcnt lgkmcnt(5)
	v_mfma_f32_32x32x16_bf16 v[66:81], v[222:225], v[248:251], v[66:81]
	global_load_lds_dwordx4 v165, s[66:67] offset:3072
	s_add_u32 m0, m0, 0x1000
	v_mfma_f32_32x32x16_bf16 v[2:17], v[226:229], v[248:251], v[2:17]
	ds_read_b128 v[248:251], v179 offset:6144
	ds_read_b128 v[222:225], v176
	ds_read_b128 v[226:229], v176 offset:4096
	s_waitcnt vmcnt(8)
	v_cvt_pk_bf16_f32 v190, v146, v150
	v_cvt_pk_bf16_f32 v191, v154, v158
	v_cvt_pk_bf16_f32 v192, v147, v151
	v_cvt_pk_bf16_f32 v193, v155, v159
	s_waitcnt lgkmcnt(5)
	v_mfma_f32_32x32x16_bf16 v[114:129], v[252:255], v[230:233], v[114:129]
	global_load_lds_dwordx4 v166, s[66:67]
	ds_write2st64_b64 v180, v[190:191], v[192:193] offset0:16 offset1:20
	v_cvt_pk_bf16_f32 v194, v148, v152
	v_cvt_pk_bf16_f32 v195, v156, v160
	v_cvt_pk_bf16_f32 v190, v149, v153
	v_cvt_pk_bf16_f32 v191, v157, v161
	v_mfma_f32_32x32x16_bf16 v[50:65], v[170:173], v[230:233], v[50:65]
	global_load_lds_dwordx4 v167, s[66:67] offset:1024
	ds_write2st64_b64 v180, v[194:195], v[190:191] offset0:24 offset1:28
	s_add_i32 s0, s0, 1
	s_and_b32 s58, s0, 31
	s_lshl_b32 s58, s58, 17
	s_add_u32 s58, s4, s58
	s_addc_u32 s59, s5, 0
	s_add_u32 s60, s58, 0x1000
	s_addc_u32 s61, s59, 0
	s_add_u32 s62, s58, s33
	s_addc_u32 s63, s59, 0
	s_add_u32 s64, s58, 0x3000
	s_addc_u32 s65, s59, 0
	s_waitcnt lgkmcnt(6)
	v_mfma_f32_32x32x16_bf16 v[98:113], v[252:255], v[234:237], v[98:113]
	global_load_lds_dwordx4 v168, s[66:67] offset:2048
	v_mfma_f32_32x32x16_bf16 v[34:49], v[170:173], v[234:237], v[34:49]
	global_load_lds_dwordx4 v169, s[66:67] offset:3072
	s_waitcnt lgkmcnt(5)
	v_mfma_f32_32x32x16_bf16 v[82:97], v[252:255], v[238:241], v[82:97]
	global_load_dwordx4 v[146:149], v181, s[58:59]
	v_mfma_f32_32x32x16_bf16 v[18:33], v[170:173], v[238:241], v[18:33]
	global_load_dwordx4 v[150:153], v181, s[60:61]
	s_waitcnt lgkmcnt(4)
	v_mfma_f32_32x32x16_bf16 v[66:81], v[252:255], v[248:251], v[66:81]
	global_load_dwordx4 v[154:157], v181, s[62:63]
	v_mfma_f32_32x32x16_bf16 v[2:17], v[170:173], v[248:251], v[2:17]
	global_load_dwordx4 v[158:161], v181, s[64:65]
	s_waitcnt lgkmcnt(0)
	s_barrier
	ds_read_b128 v[230:233], v178 offset:8192
	ds_read_b128 v[234:237], v178 offset:10240
	ds_read_b128 v[238:241], v178 offset:12288
	ds_read_b128 v[248:251], v178 offset:14336
	ds_read_b128 v[252:255], v177
	ds_read_b128 v[170:173], v177 offset:4096
	s_cmp_eq_u32 s46, 14
	s_cbranch_scc1 .Lg7_switch
.Lg7_noswitch:
	s_waitcnt lgkmcnt(5)
	v_mfma_f32_32x32x16_bf16 v[114:129], v[222:225], v[230:233], v[114:129]
	v_mfma_f32_32x32x16_bf16 v[50:65], v[226:229], v[230:233], v[50:65]
	ds_read_b128 v[230:233], v179 offset:8192
	s_waitcnt lgkmcnt(5)
	v_mfma_f32_32x32x16_bf16 v[98:113], v[222:225], v[234:237], v[98:113]
	v_mfma_f32_32x32x16_bf16 v[34:49], v[226:229], v[234:237], v[34:49]
	ds_read_b128 v[234:237], v179 offset:10240
	s_waitcnt lgkmcnt(5)
	v_mfma_f32_32x32x16_bf16 v[82:97], v[222:225], v[238:241], v[82:97]
	v_mfma_f32_32x32x16_bf16 v[18:33], v[226:229], v[238:241], v[18:33]
	ds_read_b128 v[238:241], v179 offset:12288
	s_waitcnt lgkmcnt(5)
	v_mfma_f32_32x32x16_bf16 v[66:81], v[222:225], v[248:251], v[66:81]
	v_mfma_f32_32x32x16_bf16 v[2:17], v[226:229], v[248:251], v[2:17]
	ds_read_b128 v[248:251], v179 offset:14336
	s_waitcnt vmcnt(12)
	v_cvt_pk_bf16_f32 v190, v130, v134
	v_cvt_pk_bf16_f32 v191, v138, v142
	v_cvt_pk_bf16_f32 v192, v131, v135
	v_cvt_pk_bf16_f32 v193, v139, v143
	s_waitcnt lgkmcnt(3)
	v_mfma_f32_32x32x16_bf16 v[114:129], v[252:255], v[230:233], v[114:129]
	ds_write2st64_b64 v180, v[190:191], v[192:193] offset0:0 offset1:4
	v_cvt_pk_bf16_f32 v194, v132, v136
	v_cvt_pk_bf16_f32 v195, v140, v144
	v_cvt_pk_bf16_f32 v190, v133, v137
	v_cvt_pk_bf16_f32 v191, v141, v145
	v_mfma_f32_32x32x16_bf16 v[50:65], v[170:173], v[230:233], v[50:65]
	ds_write2st64_b64 v180, v[194:195], v[190:191] offset0:8 offset1:12
	s_lshl_b32 s0, s39, 1
	s_add_i32 s0, s0, s74
	s_add_i32 s0, s0, 2
	s_and_b32 s58, s0, 31
	s_lshl_b32 s58, s58, 17
	s_add_u32 s58, s4, s58
	s_addc_u32 s59, s5, 0
	s_add_u32 s60, s58, 0x1000
	s_addc_u32 s61, s59, 0
	s_add_u32 s62, s58, s33
	s_addc_u32 s63, s59, 0
	s_add_u32 s64, s58, 0x3000
	s_addc_u32 s65, s59, 0
	s_waitcnt lgkmcnt(4)
	v_mfma_f32_32x32x16_bf16 v[98:113], v[252:255], v[234:237], v[98:113]
	v_mfma_f32_32x32x16_bf16 v[34:49], v[170:173], v[234:237], v[34:49]
	s_waitcnt lgkmcnt(3)
	v_mfma_f32_32x32x16_bf16 v[82:97], v[252:255], v[238:241], v[82:97]
	global_load_dwordx4 v[130:133], v181, s[58:59]
	v_mfma_f32_32x32x16_bf16 v[18:33], v[170:173], v[238:241], v[18:33]
	global_load_dwordx4 v[134:137], v181, s[60:61]
	s_waitcnt lgkmcnt(2)
	v_mfma_f32_32x32x16_bf16 v[66:81], v[252:255], v[248:251], v[66:81]
	global_load_dwordx4 v[138:141], v181, s[62:63]
	v_mfma_f32_32x32x16_bf16 v[2:17], v[170:173], v[248:251], v[2:17]
	global_load_dwordx4 v[142:145], v181, s[64:65]
	s_xor_b32 s76, s76, 0x2000
	v_xor_b32_e32 v174, 0x2000, v174
	v_xor_b32_e32 v175, 0x2000, v175
	v_xor_b32_e32 v176, 0x2000, v176
	v_xor_b32_e32 v177, 0x2000, v177
	s_waitcnt vmcnt(8)
	ds_read_b128 v[222:225], v174
	ds_read_b128 v[226:229], v174 offset:4096
	s_add_i32 s74, s74, 2
	s_add_i32 s46, s46, 1
	s_cmp_lt_u32 s46, 16
	s_cbranch_scc1 .Lg7_loop
	s_branch .LBB0_1417
